# adds: top-k threshold search trimmed, PV fragment reads pipelined through 4 buffers, selected-branch accumulators kept in place
# speedup vs baseline: 1.0346x; 1.0094x over previous
.LBB0_822:
	s_or_b64 exec, exec, s[18:19]
	s_mul_i32 s18, s64, 0x3000
	v_add_u32_e32 v0, s18, v182
	ds_read_b64_tr_b16 v[238:239], v0 offset:18432
	ds_read_b64_tr_b16 v[240:241], v0 offset:19200
	ds_read_b64_tr_b16 v[242:243], v0 offset:18496
	ds_read_b64_tr_b16 v[244:245], v0 offset:19264
	ds_read_b64_tr_b16 v[246:247], v0 offset:21504
	ds_read_b64_tr_b16 v[248:249], v0 offset:22272
	ds_read_b64_tr_b16 v[250:251], v0 offset:21568
	ds_read_b64_tr_b16 v[252:253], v0 offset:22336
	v_cvt_pk_bf16_f32 v50, v50, v51
	v_cvt_pk_bf16_f32 v51, v52, v53
	v_cvt_pk_bf16_f32 v52, v54, v55
	v_cvt_pk_bf16_f32 v53, v100, v101
	v_cvt_pk_bf16_f32 v34, v34, v35
	v_cvt_pk_bf16_f32 v35, v36, v37
	s_nop 0
	s_waitcnt lgkmcnt(6)
	v_mfma_f32_32x32x16_bf16 v[2:17], v[238:241], v[50:53], v[2:17]
	ds_read_b64_tr_b16 v[238:239], v0 offset:24576
	ds_read_b64_tr_b16 v[240:241], v0 offset:25344
	v_cvt_pk_bf16_f32 v36, v38, v39
	v_cvt_pk_bf16_f32 v37, v40, v41
	s_nop 0
	s_waitcnt lgkmcnt(6)
	v_mfma_f32_32x32x16_bf16 v[18:33], v[242:245], v[50:53], v[18:33]
	ds_read_b64_tr_b16 v[242:243], v0 offset:24640
	ds_read_b64_tr_b16 v[244:245], v0 offset:25408
	v_cvt_pk_bf16_f32 v50, v56, v57
	v_cvt_pk_bf16_f32 v51, v58, v59
	v_cvt_pk_bf16_f32 v52, v60, v61
	v_cvt_pk_bf16_f32 v53, v62, v63
	s_nop 0
	s_nop 0
	s_waitcnt lgkmcnt(6)
	v_mfma_f32_32x32x16_bf16 v[2:17], v[246:249], v[50:53], v[2:17]
	ds_read_b64_tr_b16 v[246:247], v0 offset:27648
	ds_read_b64_tr_b16 v[248:249], v0 offset:28416
	s_nop 0
	s_waitcnt lgkmcnt(6)
	v_mfma_f32_32x32x16_bf16 v[18:33], v[250:253], v[50:53], v[18:33]
	ds_read_b64_tr_b16 v[250:251], v0 offset:27712
	ds_read_b64_tr_b16 v[252:253], v0 offset:28480
	s_nop 0
	s_waitcnt lgkmcnt(6)
	v_mfma_f32_32x32x16_bf16 v[2:17], v[238:241], v[34:37], v[2:17]
	s_nop 0
	s_waitcnt lgkmcnt(4)
	v_mfma_f32_32x32x16_bf16 v[18:33], v[242:245], v[34:37], v[18:33]
	v_cvt_pk_bf16_f32 v34, v42, v43
	v_cvt_pk_bf16_f32 v35, v44, v45
	v_cvt_pk_bf16_f32 v36, v46, v47
	v_cvt_pk_bf16_f32 v37, v48, v49
	s_nop 0
	s_nop 0
	s_waitcnt lgkmcnt(2)
	v_mfma_f32_32x32x16_bf16 v[2:17], v[246:249], v[34:37], v[2:17]
	s_nop 0
	s_waitcnt lgkmcnt(0)
	v_mfma_f32_32x32x16_bf16 v[18:33], v[250:253], v[34:37], v[18:33]
	s_branch .LBB0_824

.LBB0_833:
	s_or_b64 exec, exec, s[12:13]
	s_mov_b32 s12, 0
	s_or_b32 s13, s12, 0x10000000
	v_cmp_le_u32_e64 s[10:11], s13, v3
	s_bcnt1_i32_b64 s30, s[10:11]
	s_cmp_gt_u32 s30, 15
	s_cselect_b32 s12, s13, s12
	s_or_b32 s13, s12, 0x8000000
	v_cmp_le_u32_e64 s[10:11], s13, v3
	s_bcnt1_i32_b64 s30, s[10:11]
	s_cmp_gt_u32 s30, 15
	s_cselect_b32 s12, s13, s12
	s_or_b32 s13, s12, 0x4000000
	v_cmp_le_u32_e64 s[10:11], s13, v3
	s_bcnt1_i32_b64 s30, s[10:11]
	s_cmp_gt_u32 s30, 15
	s_cselect_b32 s12, s13, s12
	s_or_b32 s13, s12, 0x2000000
	v_cmp_le_u32_e64 s[10:11], s13, v3
	s_bcnt1_i32_b64 s30, s[10:11]
	s_cmp_gt_u32 s30, 15
	s_cselect_b32 s12, s13, s12
	s_or_b32 s13, s12, 0x1000000
	v_cmp_le_u32_e64 s[10:11], s13, v3
	s_bcnt1_i32_b64 s30, s[10:11]
	s_cmp_gt_u32 s30, 15
	s_cselect_b32 s12, s13, s12
	s_or_b32 s13, s12, 0x800000
	v_cmp_le_u32_e64 s[10:11], s13, v3
	s_bcnt1_i32_b64 s30, s[10:11]
	s_cmp_gt_u32 s30, 15
	s_cselect_b32 s12, s13, s12
	s_or_b32 s13, s12, 0x400000
	v_cmp_le_u32_e64 s[10:11], s13, v3
	s_bcnt1_i32_b64 s30, s[10:11]
	s_cmp_gt_u32 s30, 15
	s_cselect_b32 s12, s13, s12
	s_or_b32 s13, s12, 0x200000
	v_cmp_le_u32_e64 s[10:11], s13, v3
	s_bcnt1_i32_b64 s30, s[10:11]
	s_cmp_gt_u32 s30, 15
	s_cselect_b32 s12, s13, s12
	s_or_b32 s13, s12, 0x100000
	v_cmp_le_u32_e64 s[10:11], s13, v3
	s_bcnt1_i32_b64 s30, s[10:11]
	s_cmp_gt_u32 s30, 15
	s_cselect_b32 s12, s13, s12
	s_or_b32 s13, s12, 0x80000
	v_cmp_le_u32_e64 s[10:11], s13, v3
	s_bcnt1_i32_b64 s30, s[10:11]
	s_cmp_gt_u32 s30, 15
	s_cselect_b32 s12, s13, s12
	s_or_b32 s13, s12, 0x40000
	v_cmp_le_u32_e64 s[10:11], s13, v3
	s_bcnt1_i32_b64 s30, s[10:11]
	s_cmp_gt_u32 s30, 15
	s_cselect_b32 s12, s13, s12
	s_or_b32 s13, s12, 0x20000
	v_cmp_le_u32_e64 s[10:11], s13, v3
	s_bcnt1_i32_b64 s30, s[10:11]
	s_cmp_gt_u32 s30, 15
	s_cselect_b32 s12, s13, s12
	s_or_b32 s13, s12, 0x10000
	v_cmp_le_u32_e64 s[10:11], s13, v3
	s_bcnt1_i32_b64 s30, s[10:11]
	s_cmp_gt_u32 s30, 15
	s_cselect_b32 s12, s13, s12
	s_or_b32 s13, s12, 0x8000
	v_cmp_le_u32_e64 s[10:11], s13, v3
	s_bcnt1_i32_b64 s30, s[10:11]
	s_cmp_gt_u32 s30, 15
	s_cselect_b32 s12, s13, s12
	s_or_b32 s13, s12, 0x4000
	v_cmp_le_u32_e64 s[10:11], s13, v3
	s_bcnt1_i32_b64 s30, s[10:11]
	s_cmp_gt_u32 s30, 15
	s_cselect_b32 s12, s13, s12
	s_or_b32 s13, s12, 0x2000
	v_cmp_le_u32_e64 s[10:11], s13, v3
	s_bcnt1_i32_b64 s30, s[10:11]
	s_cmp_gt_u32 s30, 15
	s_cselect_b32 s12, s13, s12
	s_or_b32 s13, s12, 0x1000
	v_cmp_le_u32_e64 s[10:11], s13, v3
	s_bcnt1_i32_b64 s30, s[10:11]
	s_cmp_gt_u32 s30, 15
	s_cselect_b32 s12, s13, s12
	s_or_b32 s13, s12, 0x800
	v_cmp_le_u32_e64 s[10:11], s13, v3
	s_bcnt1_i32_b64 s30, s[10:11]
	s_cmp_gt_u32 s30, 15
	s_cselect_b32 s12, s13, s12
	s_or_b32 s13, s12, 0x400
	v_cmp_le_u32_e64 s[10:11], s13, v3
	s_bcnt1_i32_b64 s30, s[10:11]
	s_cmp_gt_u32 s30, 15
	s_cselect_b32 s12, s13, s12
	s_or_b32 s13, s12, 0x200
	v_cmp_le_u32_e64 s[10:11], s13, v3
	s_bcnt1_i32_b64 s30, s[10:11]
	s_cmp_gt_u32 s30, 15
	s_cselect_b32 s12, s13, s12
	s_or_b32 s13, s12, 0x100
	v_cmp_le_u32_e64 s[10:11], s13, v3
	s_bcnt1_i32_b64 s30, s[10:11]
	s_cmp_gt_u32 s30, 15
	s_cselect_b32 s12, s13, s12
	s_or_b32 s13, s12, 0x80
	v_cmp_le_u32_e64 s[10:11], s13, v3
	s_bcnt1_i32_b64 s30, s[10:11]
	s_cmp_gt_u32 s30, 15
	s_cselect_b32 s12, s13, s12
	s_or_b32 s13, s12, 64
	v_cmp_le_u32_e64 s[10:11], s13, v3
	s_bcnt1_i32_b64 s30, s[10:11]
	s_cmp_gt_u32 s30, 15
	s_cselect_b32 s12, s13, s12
	s_or_b32 s13, s12, 32
	v_cmp_le_u32_e64 s[10:11], s13, v3
	s_bcnt1_i32_b64 s30, s[10:11]
	s_cmp_gt_u32 s30, 15
	s_cselect_b32 s12, s13, s12
	s_or_b32 s13, s12, 16
	v_cmp_le_u32_e64 s[10:11], s13, v3
	s_bcnt1_i32_b64 s30, s[10:11]
	s_cmp_gt_u32 s30, 15
	s_cselect_b32 s12, s13, s12
	s_or_b32 s13, s12, 8
	v_cmp_le_u32_e64 s[10:11], s13, v3
	s_bcnt1_i32_b64 s30, s[10:11]
	s_cmp_gt_u32 s30, 15
	s_cselect_b32 s12, s13, s12
	s_or_b32 s13, s12, 4
	v_cmp_le_u32_e64 s[10:11], s13, v3
	s_bcnt1_i32_b64 s30, s[10:11]
	s_cmp_gt_u32 s30, 15
	s_cselect_b32 s12, s13, s12
	s_or_b32 s13, s12, 2
	v_cmp_le_u32_e64 s[10:11], s13, v3
	s_bcnt1_i32_b64 s30, s[10:11]
	s_cmp_gt_u32 s30, 15
	s_cselect_b32 s12, s13, s12
	s_or_b32 s13, s12, 1
	v_cmp_le_u32_e64 s[10:11], s13, v3
	s_bcnt1_i32_b64 s30, s[10:11]
	s_cmp_gt_u32 s30, 15
	s_cselect_b32 s12, s13, s12
	v_cmp_lt_u32_e64 s[10:11], s12, v3
	s_cmp_lg_u32 s12, 0
	s_cselect_b64 s[16:17], -1, 0
	s_bcnt1_i32_b64 s13, s[10:11]
	s_sub_i32 s18, 16, s13
	v_cmp_eq_u32_e64 s[12:13], s12, v3
	s_and_b64 s[16:17], s[16:17], s[12:13]
	v_cndmask_b32_e64 v3, 0, 1, s[16:17]
	v_cmp_ne_u32_e64 s[12:13], 0, v3
	s_nop 1
	v_mbcnt_lo_u32_b32 v3, s12, 0
	v_mbcnt_hi_u32_b32 v3, s13, v3
	v_cmp_gt_i32_e64 s[12:13], s18, v3
	s_and_b64 s[12:13], s[16:17], s[12:13]
	s_or_b64 s[10:11], s[10:11], s[12:13]
	v_cndmask_b32_e64 v3, 0, 1, s[10:11]
	v_cmp_ne_u32_e64 s[16:17], 0, v3
	s_and_saveexec_b64 s[12:13], vcc
	s_cbranch_execz .LBB0_830
	v_mov_b32_e32 v3, s21
	v_mov_b64_e32 v[4:5], s[16:17]
	s_cmp_eq_u64 s[16:17], 0
	ds_write_b64 v3, v[4:5]
	s_cbranch_scc1 .LBB0_829
	v_mbcnt_lo_u32_b32 v3, exec_lo, 0
	v_mbcnt_hi_u32_b32 v3, exec_hi, v3
	v_cmp_eq_u32_e64 s[10:11], 0, v3
	s_and_saveexec_b64 s[18:19], s[10:11]
	s_cbranch_execz .LBB0_828
	v_mov_b32_e32 v3, s85
	v_mov_b64_e32 v[4:5], s[16:17]
	ds_or_b64 v3, v[4:5]
	s_branch .LBB0_828

.LBB0_867:
	v_sub_f32_e32 v206, v137, v0
	v_exp_f32_e32 v206, v206
	v_sub_f32_e32 v207, v138, v0
	v_exp_f32_e32 v207, v207
	v_cmp_lt_f32_e32 vcc, s29, v137
	v_sub_f32_e32 v208, v136, v0
	v_exp_f32_e32 v208, v208
	v_cndmask_b32_e32 v206, 0, v206, vcc
	v_cmp_lt_f32_e32 vcc, s29, v138
	v_add_u32_e32 v218, s74, v182
	s_mov_b64 s[18:19], 0
	v_cndmask_b32_e32 v138, 0, v207, vcc
	v_sub_f32_e32 v207, v134, v0
	v_exp_f32_e32 v207, v207
	v_cmp_lt_f32_e32 vcc, s29, v134
	v_add_f32_e32 v137, 0, v138
	v_add_f32_e32 v137, v206, v137
	v_cndmask_b32_e32 v207, 0, v207, vcc
	v_cmp_lt_f32_e32 vcc, s29, v136
	v_sub_f32_e32 v136, v135, v0
	v_exp_f32_e32 v136, v136
	v_cndmask_b32_e32 v208, 0, v208, vcc
	v_add_f32_e32 v134, v208, v137
	v_sub_f32_e32 v137, v187, v0
	v_exp_f32_e32 v137, v137
	v_cmp_lt_f32_e32 vcc, s29, v135
	v_sub_f32_e32 v135, v186, v0
	v_exp_f32_e32 v135, v135
	v_cndmask_b32_e32 v209, 0, v136, vcc
	v_sub_f32_e32 v136, v189, v0
	v_exp_f32_e32 v136, v136
	v_cmp_lt_f32_e32 vcc, s29, v187
	v_add_f32_e32 v134, v207, v134
	v_cvt_pk_bf16_f32 v187, v208, v207
	v_cndmask_b32_e32 v210, 0, v137, vcc
	v_cmp_lt_f32_e32 vcc, s29, v186
	v_add_f32_e32 v134, v210, v134
	v_add_f32_e32 v134, v209, v134
	v_cndmask_b32_e32 v211, 0, v135, vcc
	v_cmp_lt_f32_e32 vcc, s29, v189
	v_sub_f32_e32 v135, v188, v0
	v_exp_f32_e32 v135, v135
	v_cndmask_b32_e32 v189, 0, v136, vcc
	v_sub_f32_e32 v136, v191, v0
	v_exp_f32_e32 v136, v136
	v_cmp_lt_f32_e32 vcc, s29, v188
	v_add_f32_e32 v134, v189, v134
	v_add_f32_e32 v134, v211, v134
	v_cndmask_b32_e32 v212, 0, v135, vcc
	v_cmp_lt_f32_e32 vcc, s29, v191
	v_sub_f32_e32 v135, v190, v0
	v_exp_f32_e32 v135, v135
	v_cndmask_b32_e32 v213, 0, v136, vcc
	v_sub_f32_e32 v136, v193, v0
	v_exp_f32_e32 v136, v136
	v_cmp_lt_f32_e32 vcc, s29, v190
	v_add_f32_e32 v134, v213, v134
	v_add_f32_e32 v134, v212, v134
	v_cndmask_b32_e32 v214, 0, v135, vcc
	v_cmp_lt_f32_e32 vcc, s29, v193
	v_sub_f32_e32 v135, v192, v0
	v_exp_f32_e32 v135, v135
	v_cndmask_b32_e32 v215, 0, v136, vcc
	v_sub_f32_e32 v136, v196, v0
	v_exp_f32_e32 v136, v136
	v_cmp_lt_f32_e32 vcc, s29, v192
	v_add_f32_e32 v134, v215, v134
	v_add_f32_e32 v134, v214, v134
	v_cndmask_b32_e32 v216, 0, v135, vcc
	v_cmp_lt_f32_e32 vcc, s29, v196
	v_sub_f32_e32 v135, v194, v0
	v_exp_f32_e32 v135, v135
	v_cndmask_b32_e32 v196, 0, v136, vcc
	v_sub_f32_e32 v136, v198, v0
	v_exp_f32_e32 v136, v136
	v_cmp_lt_f32_e32 vcc, s29, v194
	v_add_f32_e32 v134, v196, v134
	v_add_f32_e32 v134, v216, v134
	v_cndmask_b32_e32 v194, 0, v135, vcc
	v_cmp_lt_f32_e32 vcc, s29, v198
	v_sub_f32_e32 v135, v195, v0
	v_exp_f32_e32 v135, v135
	v_cndmask_b32_e32 v198, 0, v136, vcc
	v_sub_f32_e32 v136, v199, v0
	v_exp_f32_e32 v136, v136
	v_cmp_lt_f32_e32 vcc, s29, v195
	v_add_f32_e32 v134, v198, v134
	v_add_f32_e32 v134, v194, v134
	v_cndmask_b32_e32 v195, 0, v135, vcc
	v_cmp_lt_f32_e32 vcc, s29, v199
	v_sub_f32_e32 v135, v197, v0
	v_exp_f32_e32 v135, v135
	v_cndmask_b32_e32 v199, 0, v136, vcc
	v_sub_f32_e32 v136, v201, v0
	v_exp_f32_e32 v136, v136
	v_cmp_lt_f32_e32 vcc, s29, v197
	v_add_f32_e32 v134, v199, v134
	v_add_f32_e32 v134, v195, v134
	v_cndmask_b32_e32 v197, 0, v135, vcc
	v_cmp_lt_f32_e32 vcc, s29, v201
	v_sub_f32_e32 v135, v200, v0
	v_exp_f32_e32 v135, v135
	v_cndmask_b32_e32 v201, 0, v136, vcc
	v_sub_f32_e32 v136, v203, v0
	v_exp_f32_e32 v136, v136
	v_cmp_lt_f32_e32 vcc, s29, v200
	v_add_f32_e32 v134, v201, v134
	v_add_f32_e32 v134, v197, v134
	v_cndmask_b32_e32 v200, 0, v135, vcc
	v_cmp_lt_f32_e32 vcc, s29, v203
	v_sub_f32_e32 v135, v202, v0
	v_exp_f32_e32 v135, v135
	v_cndmask_b32_e32 v203, 0, v136, vcc
	v_sub_f32_e32 v136, v205, v0
	v_exp_f32_e32 v136, v136
	v_cmp_lt_f32_e32 vcc, s29, v202
	v_add_f32_e32 v134, v203, v134
	v_add_f32_e32 v134, v200, v134
	v_cndmask_b32_e32 v202, 0, v135, vcc
	v_cmp_lt_f32_e32 vcc, s29, v205
	v_sub_f32_e32 v135, v139, v0
	v_exp_f32_e32 v186, v135
	v_cndmask_b32_e32 v205, 0, v136, vcc
	v_add_f32_e32 v134, v205, v134
	v_add_f32_e32 v217, v202, v134
	v_sub_f32_e32 v134, v204, v0
	v_exp_f32_e32 v134, v134
	v_cmp_lt_f32_e32 vcc, s29, v204
	v_cvt_pk_bf16_f32 v188, v210, v209
	v_cvt_pk_bf16_f32 v189, v189, v211
	v_cndmask_b32_e32 v204, 0, v134, vcc
	ds_read_b64_tr_b16 v[238:239], v218 offset:18432
	ds_read_b64_tr_b16 v[240:241], v218 offset:19200
	ds_read_b64_tr_b16 v[242:243], v218 offset:18496
	ds_read_b64_tr_b16 v[244:245], v218 offset:19264
	ds_read_b64_tr_b16 v[246:247], v218 offset:21504
	ds_read_b64_tr_b16 v[248:249], v218 offset:22272
	ds_read_b64_tr_b16 v[250:251], v218 offset:21568
	ds_read_b64_tr_b16 v[252:253], v218 offset:22336
	v_cmp_lt_f32_e32 vcc, s29, v139
	v_sub_f32_e32 v139, v132, v0
	v_exp_f32_e32 v139, v139
	v_cndmask_b32_e32 v219, 0, v186, vcc
	v_cvt_pk_bf16_f32 v186, v138, v206
	v_cmp_lt_f32_e32 vcc, s29, v132
	v_sub_f32_e32 v132, v129, v0
	s_nop 0
	s_waitcnt lgkmcnt(6)
	v_mfma_f32_32x32x16_bf16 v[34:49], v[238:241], v[186:189], v[34:49]
	ds_read_b64_tr_b16 v[238:239], v218 offset:24576
	ds_read_b64_tr_b16 v[240:241], v218 offset:25344
	v_add_f32_e32 v134, v219, v217
	v_add_f32_e32 v206, v204, v134
	v_sub_f32_e32 v134, v133, v0
	v_exp_f32_e32 v138, v134
	s_nop 0
	s_waitcnt lgkmcnt(6)
	v_mfma_f32_32x32x16_bf16 v[50:65], v[242:245], v[186:189], v[50:65]
	ds_read_b64_tr_b16 v[242:243], v218 offset:24640
	ds_read_b64_tr_b16 v[244:245], v218 offset:25408
	v_cvt_pk_bf16_f32 v186, v213, v212
	v_cvt_pk_bf16_f32 v187, v215, v214
	v_cvt_pk_bf16_f32 v188, v196, v216
	v_cvt_pk_bf16_f32 v189, v198, v194
	v_exp_f32_e32 v198, v132
	v_sub_f32_e32 v132, v131, v0
	s_nop 0
	s_waitcnt lgkmcnt(6)
	v_mfma_f32_32x32x16_bf16 v[34:49], v[246:249], v[186:189], v[34:49]
	ds_read_b64_tr_b16 v[246:247], v218 offset:27648
	ds_read_b64_tr_b16 v[248:249], v218 offset:28416
	v_cndmask_b32_e32 v194, 0, v139, vcc
	v_cmp_lt_f32_e32 vcc, s29, v133
	v_exp_f32_e32 v136, v132
	v_cndmask_b32_e32 v196, 0, v138, vcc
	v_cmp_lt_f32_e32 vcc, s29, v131
	v_sub_f32_e32 v131, v130, v0
	s_nop 0
	s_waitcnt lgkmcnt(6)
	v_mfma_f32_32x32x16_bf16 v[50:65], v[250:253], v[186:189], v[50:65]
	ds_read_b64_tr_b16 v[250:251], v218 offset:27712
	ds_read_b64_tr_b16 v[252:253], v218 offset:28480
	v_cndmask_b32_e32 v190, 0, v136, vcc
	v_cvt_pk_bf16_f32 v136, v199, v195
	v_cvt_pk_bf16_f32 v137, v201, v197
	v_cvt_pk_bf16_f32 v138, v203, v200
	v_cvt_pk_bf16_f32 v139, v205, v202
	v_exp_f32_e32 v131, v131
	v_cmp_lt_f32_e32 vcc, s29, v129
	s_nop 0
	s_waitcnt lgkmcnt(6)
	v_mfma_f32_32x32x16_bf16 v[34:49], v[238:241], v[136:139], v[34:49]
	v_sub_f32_e32 v132, v128, v0
	v_cndmask_b32_e32 v129, 0, v198, vcc
	v_exp_f32_e32 v134, v132
	v_cmp_lt_f32_e32 vcc, s29, v130
	v_cvt_pk_bf16_f32 v135, v196, v194
	s_nop 0
	v_cndmask_b32_e32 v191, 0, v131, vcc
	s_nop 0
	s_waitcnt lgkmcnt(4)
	v_mfma_f32_32x32x16_bf16 v[50:65], v[242:245], v[136:139], v[50:65]
	v_cmp_lt_f32_e32 vcc, s29, v128
	v_cvt_pk_bf16_f32 v136, v129, v190
	s_nop 0
	v_cndmask_b32_e32 v128, 0, v134, vcc
	v_cvt_pk_bf16_f32 v134, v219, v204
	v_cvt_pk_bf16_f32 v137, v128, v191
	s_nop 0
	s_nop 0
	s_waitcnt lgkmcnt(2)
	v_mfma_f32_32x32x16_bf16 v[34:49], v[246:249], v[134:137], v[34:49]
	v_add_f32_e32 v130, v196, v206
	v_add_f32_e32 v130, v194, v130
	v_add_f32_e32 v129, v129, v130
	v_add_f32_e32 v129, v190, v129
	v_add_f32_e32 v128, v128, v129
	v_add_f32_e32 v128, v191, v128
	v_add_f32_e32 v127, v128, v127
	s_nop 0
	s_waitcnt lgkmcnt(0)
	v_mfma_f32_32x32x16_bf16 v[50:65], v[250:253], v[134:137], v[50:65]

.LBB0_871:
	v_mul_f32_e64 v42, -v118, v110
	v_sub_f32_e32 v42, v0, v42
	v_sub_f32_e32 v43, v109, v42
	v_exp_f32_e32 v43, v43
	v_sub_f32_e32 v45, v108, v42
	v_exp_f32_e32 v45, v45
	v_sub_f32_e32 v46, v107, v42
	v_exp_f32_e32 v46, v46
	v_sub_f32_e32 v47, v106, v42
	v_exp_f32_e32 v47, v47
	v_sub_f32_e32 v48, v105, v42
	v_add_f32_e32 v44, 0, v43
	v_exp_f32_e32 v48, v48
	v_sub_f32_e32 v49, v104, v42
	v_add_f32_e32 v44, v45, v44
	v_exp_f32_e32 v49, v49
	v_sub_f32_e32 v62, v103, v42
	v_add_f32_e32 v44, v46, v44
	v_exp_f32_e32 v62, v62
	v_sub_f32_e32 v63, v102, v42
	v_add_f32_e32 v44, v47, v44
	v_exp_f32_e32 v63, v63
	v_sub_f32_e32 v64, v101, v42
	v_add_f32_e32 v44, v48, v44
	v_exp_f32_e32 v64, v64
	v_sub_f32_e32 v65, v100, v42
	v_add_f32_e32 v44, v49, v44
	v_exp_f32_e32 v65, v65
	v_sub_f32_e32 v99, v99, v42
	v_add_f32_e32 v44, v62, v44
	v_exp_f32_e32 v99, v99
	v_sub_f32_e32 v98, v98, v42
	v_add_f32_e32 v44, v63, v44
	v_exp_f32_e32 v98, v98
	v_sub_f32_e32 v61, v61, v42
	v_add_f32_e32 v44, v64, v44
	v_exp_f32_e32 v61, v61
	v_sub_f32_e32 v60, v60, v42
	v_add_f32_e32 v44, v65, v44
	v_exp_f32_e32 v60, v60
	v_sub_f32_e32 v59, v59, v42
	v_add_f32_e32 v44, v99, v44
	v_exp_f32_e32 v59, v59
	v_sub_f32_e32 v58, v58, v42
	v_add_f32_e32 v44, v98, v44
	v_exp_f32_e32 v58, v58
	v_sub_f32_e32 v57, v57, v42
	v_add_f32_e32 v44, v61, v44
	v_exp_f32_e32 v57, v57
	v_sub_f32_e32 v56, v56, v42
	v_add_f32_e32 v44, v60, v44
	v_exp_f32_e32 v56, v56
	v_sub_f32_e32 v55, v55, v42
	v_add_f32_e32 v44, v59, v44
	v_exp_f32_e32 v55, v55
	v_sub_f32_e32 v54, v54, v42
	v_add_f32_e32 v44, v58, v44
	v_exp_f32_e32 v54, v54
	v_sub_f32_e32 v53, v53, v42
	v_add_f32_e32 v44, v57, v44
	v_exp_f32_e32 v53, v53
	v_sub_f32_e32 v52, v52, v42
	v_add_f32_e32 v44, v56, v44
	v_exp_f32_e32 v52, v52
	v_sub_f32_e32 v51, v51, v42
	v_add_f32_e32 v44, v55, v44
	v_exp_f32_e32 v51, v51
	v_sub_f32_e32 v50, v50, v42
	v_add_f32_e32 v44, v54, v44
	v_exp_f32_e32 v50, v50
	v_sub_f32_e32 v41, v41, v42
	v_add_f32_e32 v44, v53, v44
	v_exp_f32_e32 v100, v41
	v_add_f32_e32 v44, v52, v44
	v_add_f32_e32 v44, v51, v44
	v_add_f32_e32 v44, v50, v44
	v_sub_f32_e32 v40, v40, v42
	v_add_f32_e32 v41, v100, v44
	v_exp_f32_e32 v44, v40
	v_sub_f32_e32 v39, v39, v42
	v_exp_f32_e32 v101, v39
	v_sub_f32_e32 v38, v38, v42
	v_exp_f32_e32 v102, v38
	v_sub_f32_e32 v37, v37, v42
	v_exp_f32_e32 v103, v37
	v_sub_f32_e32 v36, v36, v42
	v_add_f32_e32 v40, v44, v41
	v_exp_f32_e32 v104, v36
	v_sub_f32_e32 v35, v35, v42
	v_add_f32_e32 v39, v101, v40
	v_exp_f32_e32 v105, v35
	v_sub_f32_e32 v34, v34, v42
	v_add_f32_e32 v38, v102, v39
	v_exp_f32_e32 v42, v34
	v_add_u32_e32 v106, s74, v182
	v_add_f32_e32 v37, v103, v38
	ds_read_b64_tr_b16 v[238:239], v106 offset:18432
	ds_read_b64_tr_b16 v[240:241], v106 offset:19200
	ds_read_b64_tr_b16 v[242:243], v106 offset:18496
	ds_read_b64_tr_b16 v[244:245], v106 offset:19264
	ds_read_b64_tr_b16 v[246:247], v106 offset:21504
	ds_read_b64_tr_b16 v[248:249], v106 offset:22272
	ds_read_b64_tr_b16 v[250:251], v106 offset:21568
	ds_read_b64_tr_b16 v[252:253], v106 offset:22336
	v_add_f32_e32 v36, v104, v37
	v_add_f32_e32 v35, v105, v36
	v_add_f32_e32 v34, v42, v35
	v_add_f32_e32 v127, v34, v124
	v_cvt_pk_bf16_f32 v34, v43, v45
	v_cvt_pk_bf16_f32 v35, v46, v47
	v_cvt_pk_bf16_f32 v36, v48, v49
	v_cvt_pk_bf16_f32 v37, v62, v63
	s_nop 0
	s_nop 0
	s_waitcnt lgkmcnt(6)
	v_mfma_f32_32x32x16_bf16 v[2:17], v[238:241], v[34:37], v[2:17]
	ds_read_b64_tr_b16 v[238:239], v106 offset:24576
	ds_read_b64_tr_b16 v[240:241], v106 offset:25344
	s_nop 0
	s_waitcnt lgkmcnt(6)
	v_mfma_f32_32x32x16_bf16 v[18:33], v[242:245], v[34:37], v[18:33]
	ds_read_b64_tr_b16 v[242:243], v106 offset:24640
	ds_read_b64_tr_b16 v[244:245], v106 offset:25408
	v_cvt_pk_bf16_f32 v34, v64, v65
	v_cvt_pk_bf16_f32 v35, v99, v98
	v_cvt_pk_bf16_f32 v36, v61, v60
	v_cvt_pk_bf16_f32 v37, v59, v58
	s_nop 0
	s_nop 0
	s_waitcnt lgkmcnt(6)
	v_mfma_f32_32x32x16_bf16 v[2:17], v[246:249], v[34:37], v[2:17]
	ds_read_b64_tr_b16 v[246:247], v106 offset:27648
	ds_read_b64_tr_b16 v[248:249], v106 offset:28416
	s_nop 0
	s_waitcnt lgkmcnt(6)
	v_mfma_f32_32x32x16_bf16 v[18:33], v[250:253], v[34:37], v[18:33]
	ds_read_b64_tr_b16 v[250:251], v106 offset:27712
	ds_read_b64_tr_b16 v[252:253], v106 offset:28480
	v_cvt_pk_bf16_f32 v34, v57, v56
	v_cvt_pk_bf16_f32 v35, v55, v54
	v_cvt_pk_bf16_f32 v36, v53, v52
	v_cvt_pk_bf16_f32 v37, v51, v50
	s_nop 0
	s_nop 0
	s_waitcnt lgkmcnt(6)
	v_mfma_f32_32x32x16_bf16 v[2:17], v[238:241], v[34:37], v[2:17]
	s_nop 0
	s_waitcnt lgkmcnt(4)
	v_mfma_f32_32x32x16_bf16 v[18:33], v[242:245], v[34:37], v[18:33]
	v_cvt_pk_bf16_f32 v34, v100, v44
	v_cvt_pk_bf16_f32 v35, v101, v102
	v_cvt_pk_bf16_f32 v36, v103, v104
	v_cvt_pk_bf16_f32 v37, v105, v42
	s_nop 0
	s_nop 0
	s_waitcnt lgkmcnt(2)
	v_mfma_f32_32x32x16_bf16 v[2:17], v[246:249], v[34:37], v[2:17]
	s_nop 0
	s_waitcnt lgkmcnt(0)
	v_mfma_f32_32x32x16_bf16 v[18:33], v[250:253], v[34:37], v[18:33]
	s_nop 11
	v_mov_b64_e32 v[64:65], v[32:33]
	v_mov_b64_e32 v[62:63], v[30:31]
	v_mov_b64_e32 v[60:61], v[28:29]
	v_mov_b64_e32 v[58:59], v[26:27]
	v_mov_b64_e32 v[56:57], v[24:25]
	v_mov_b64_e32 v[54:55], v[22:23]
	v_mov_b64_e32 v[52:53], v[20:21]
	v_mov_b64_e32 v[50:51], v[18:19]
	v_mov_b64_e32 v[48:49], v[16:17]
	v_mov_b64_e32 v[46:47], v[14:15]
	v_mov_b64_e32 v[44:45], v[12:13]
	v_mov_b64_e32 v[42:43], v[10:11]
	v_mov_b64_e32 v[40:41], v[8:9]
	v_mov_b64_e32 v[38:39], v[6:7]
	v_mov_b64_e32 v[36:37], v[4:5]
	v_mov_b64_e32 v[34:35], v[2:3]

.LBB0_878:
	v_mov_b32_e32 v0, v165
	s_lshl_b32 s2, s30, 6
	v_ashrrev_i32_e32 v34, 3, v0
	v_add_u32_e32 v34, s2, v34
	v_ashrrev_i32_e32 v35, 31, v34
	v_lshlrev_b64 v[34:35], 11, v[34:35]
	v_lshlrev_b32_e32 v0, 4, v0
	v_lshl_add_u64 v[34:35], s[14:15], 0, v[34:35]
	v_and_b32_e32 v0, 0x70, v0
	v_lshl_add_u64 v[34:35], v[34:35], 0, v[0:1]
	v_mov_b32_e32 v0, v165
	global_load_dwordx4 v[90:93], v[34:35], off
	s_nop 0
	v_ashrrev_i32_e32 v34, 3, v0
	v_add_u32_e32 v34, s2, v34
	v_ashrrev_i32_e32 v35, 31, v34
	v_lshlrev_b64 v[34:35], 11, v[34:35]
	v_lshlrev_b32_e32 v0, 4, v0
	v_lshl_add_u64 v[34:35], s[16:17], 0, v[34:35]
	v_and_b32_e32 v0, 0x70, v0
	v_lshl_add_u64 v[34:35], v[34:35], 0, v[0:1]
	global_load_dwordx4 v[94:97], v[34:35], off
	s_ashr_i32 s2, s67, 6
	v_lshl_add_u32 v0, s2, 3, v185
	ds_read_b64 v[34:35], v0 offset:59904
	s_waitcnt lgkmcnt(0)
	v_lshrrev_b64 v[34:35], s67, v[34:35]
	v_and_b32_e32 v0, 1, v34
	v_cmp_eq_u32_e64 s[10:11], 1, v0
	v_cmp_ne_u32_e32 vcc, 0, v0
	s_cbranch_vccz .LBB0_888
	s_lshl_b32 s3, s67, 6
	s_or_b32 s2, s3, 63
	s_cmp_gt_i32 s2, s25
	s_mul_i32 s2, s64, 0x2400
	v_add_u32_e32 v192, s2, v184
	ds_read_b128 v[98:101], v192
	ds_read_b128 v[102:105], v192 offset:32
	ds_read_b128 v[106:109], v192 offset:64
	ds_read_b128 v[110:113], v192 offset:96
	v_add_u32_e32 v0, s3, v120
	s_mul_i32 s2, s64, 0x3000
	s_mov_b64 s[18:19], -1
	v_sub_u32_e32 v190, v187, v0
	s_cbranch_scc1 .LBB0_883
	s_waitcnt lgkmcnt(3)
	v_mfma_f32_32x32x16_bf16 v[50:65], v[98:101], v[66:69], 0
	ds_read_b128 v[34:37], v192 offset:4608
	ds_read_b128 v[194:197], v192 offset:4640
	v_mov_b32_e32 v0, v190
	v_mov_b32_e32 v201, v188
	s_waitcnt lgkmcnt(1)
	v_mfma_f32_32x32x16_bf16 v[34:49], v[34:37], v[66:69], 0
	v_mfma_f32_32x32x16_bf16 v[50:65], v[102:105], v[70:73], v[50:65]
	s_waitcnt lgkmcnt(0)
	v_mfma_f32_32x32x16_bf16 v[34:49], v[194:197], v[70:73], v[34:49]
	ds_read_b128 v[194:197], v192 offset:4672
	v_mfma_f32_32x32x16_bf16 v[50:65], v[106:109], v[74:77], v[50:65]
	s_waitcnt lgkmcnt(0)
	v_mfma_f32_32x32x16_bf16 v[34:49], v[194:197], v[74:77], v[34:49]
	ds_read_b128 v[194:197], v192 offset:4704
	s_nop 0
	v_cvt_f32_i32_e32 v225, v0
	v_mfma_f32_32x32x16_bf16 v[50:65], v[110:113], v[78:81], v[50:65]
	s_waitcnt lgkmcnt(0)
	v_mfma_f32_32x32x16_bf16 v[34:49], v[194:197], v[78:81], v[34:49]
	s_nop 9
	v_add_f32_e32 v224, v148, v50
	v_add_f32_e32 v223, v118, v51
	v_max3_f32 v0, v224, s28, v223
	v_add_f32_e32 v222, v149, v52
	v_add_f32_e32 v221, v150, v53
	v_max3_f32 v0, v0, v222, v221
	v_add_f32_e32 v220, v151, v54
	v_add_f32_e32 v219, v152, v55
	v_max3_f32 v0, v0, v220, v219
	v_add_f32_e32 v218, v153, v56
	v_add_f32_e32 v217, v154, v57
	v_max3_f32 v0, v0, v218, v217
	v_add_f32_e32 v216, v155, v58
	v_add_f32_e32 v215, v156, v59
	v_max3_f32 v0, v0, v216, v215
	v_add_f32_e32 v214, v157, v60
	v_add_f32_e32 v213, v158, v61
	v_max3_f32 v0, v0, v214, v213
	v_add_f32_e32 v212, v159, v62
	v_add_f32_e32 v211, v160, v63
	v_max3_f32 v0, v0, v212, v211
	v_add_f32_e32 v210, v161, v64
	v_add_f32_e32 v209, v162, v65
	v_max3_f32 v0, v0, v210, v209
	v_add_f32_e32 v208, v163, v34
	v_add_f32_e32 v207, v166, v35
	v_max3_f32 v0, v0, v208, v207
	v_add_f32_e32 v206, v167, v36
	v_add_f32_e32 v205, v168, v37
	v_max3_f32 v0, v0, v206, v205
	v_add_f32_e32 v204, v169, v38
	v_add_f32_e32 v203, v170, v39
	v_max3_f32 v0, v0, v204, v203
	v_add_f32_e32 v202, v171, v40
	v_add_f32_e32 v200, v172, v41
	v_max3_f32 v0, v0, v202, v200
	v_add_f32_e32 v199, v173, v42
	v_add_f32_e32 v198, v174, v43
	v_max3_f32 v0, v0, v199, v198
	v_add_f32_e32 v197, v175, v44
	v_add_f32_e32 v196, v176, v45
	v_max3_f32 v0, v0, v197, v196
	v_add_f32_e32 v195, v177, v46
	v_add_f32_e32 v194, v178, v47
	v_max3_f32 v0, v0, v195, v194
	v_add_f32_e32 v193, v179, v48
	v_add_f32_e32 v191, v180, v49
	v_max3_f32 v0, v0, v193, v191
	v_fma_f32 v0, -v118, v225, v0
	v_cndmask_b32_e64 v0, v144, v0, s[10:11]
	ds_bpermute_b32 v34, v186, v0
	s_waitcnt lgkmcnt(0)
	v_max3_f32 v0, v189, v0, v34
	v_cmp_gt_f32_e32 vcc, v0, v189
	s_cbranch_vccz .LBB0_882
	v_sub_f32_e32 v34, v189, v0
	v_exp_f32_e32 v34, v34
	s_nop 0
	v_mul_f32_e32 v201, v188, v34
	v_pk_mul_f32 v[32:33], v[32:33], v[34:35] op_sel_hi:[1,0]
	v_pk_mul_f32 v[30:31], v[30:31], v[34:35] op_sel_hi:[1,0]
	v_pk_mul_f32 v[28:29], v[28:29], v[34:35] op_sel_hi:[1,0]
	v_pk_mul_f32 v[26:27], v[26:27], v[34:35] op_sel_hi:[1,0]
	v_pk_mul_f32 v[24:25], v[24:25], v[34:35] op_sel_hi:[1,0]
	v_pk_mul_f32 v[22:23], v[22:23], v[34:35] op_sel_hi:[1,0]
	v_pk_mul_f32 v[20:21], v[20:21], v[34:35] op_sel_hi:[1,0]
	v_pk_mul_f32 v[18:19], v[18:19], v[34:35] op_sel_hi:[1,0]
	v_pk_mul_f32 v[16:17], v[16:17], v[34:35] op_sel_hi:[1,0]
	v_pk_mul_f32 v[14:15], v[14:15], v[34:35] op_sel_hi:[1,0]
	v_pk_mul_f32 v[12:13], v[12:13], v[34:35] op_sel_hi:[1,0]
	v_pk_mul_f32 v[10:11], v[10:11], v[34:35] op_sel_hi:[1,0]
	v_pk_mul_f32 v[8:9], v[8:9], v[34:35] op_sel_hi:[1,0]
	v_pk_mul_f32 v[6:7], v[6:7], v[34:35] op_sel_hi:[1,0]
	v_pk_mul_f32 v[4:5], v[4:5], v[34:35] op_sel_hi:[1,0]
	v_pk_mul_f32 v[2:3], v[2:3], v[34:35] op_sel_hi:[1,0]
.LBB0_882:
	v_mul_f32_e64 v225, -v118, v225
	v_sub_f32_e32 v225, v0, v225
	v_cndmask_b32_e64 v225, v146, v225, s[10:11]
	v_sub_f32_e32 v224, v224, v225
	v_exp_f32_e32 v224, v224
	v_sub_f32_e32 v223, v223, v225
	v_exp_f32_e32 v223, v223
	v_sub_f32_e32 v222, v222, v225
	v_exp_f32_e32 v222, v222
	v_sub_f32_e32 v221, v221, v225
	v_exp_f32_e32 v221, v221
	v_sub_f32_e32 v220, v220, v225
	v_add_f32_e32 v229, 0, v224
	v_exp_f32_e32 v220, v220
	v_sub_f32_e32 v219, v219, v225
	v_add_f32_e32 v229, v223, v229
	v_exp_f32_e32 v219, v219
	v_sub_f32_e32 v218, v218, v225
	v_add_f32_e32 v229, v222, v229
	v_exp_f32_e32 v218, v218
	v_sub_f32_e32 v217, v217, v225
	v_add_f32_e32 v229, v221, v229
	v_exp_f32_e32 v217, v217
	v_sub_f32_e32 v216, v216, v225
	v_add_f32_e32 v229, v220, v229
	v_exp_f32_e32 v216, v216
	v_sub_f32_e32 v215, v215, v225
	v_add_f32_e32 v229, v219, v229
	v_exp_f32_e32 v215, v215
	v_sub_f32_e32 v214, v214, v225
	v_add_f32_e32 v229, v218, v229
	v_exp_f32_e32 v214, v214
	v_sub_f32_e32 v213, v213, v225
	v_add_f32_e32 v229, v217, v229
	v_exp_f32_e32 v213, v213
	v_sub_f32_e32 v212, v212, v225
	v_add_f32_e32 v229, v216, v229
	v_exp_f32_e32 v212, v212
	v_sub_f32_e32 v211, v211, v225
	v_add_f32_e32 v229, v215, v229
	v_exp_f32_e32 v211, v211
	v_sub_f32_e32 v210, v210, v225
	v_add_f32_e32 v229, v214, v229
	v_exp_f32_e32 v210, v210
	v_sub_f32_e32 v209, v209, v225
	v_add_f32_e32 v229, v213, v229
	v_exp_f32_e32 v209, v209
	v_sub_f32_e32 v208, v208, v225
	v_add_f32_e32 v229, v212, v229
	v_exp_f32_e32 v208, v208
	v_sub_f32_e32 v207, v207, v225
	v_add_f32_e32 v229, v211, v229
	v_exp_f32_e32 v207, v207
	v_sub_f32_e32 v206, v206, v225
	v_add_f32_e32 v229, v210, v229
	v_exp_f32_e32 v206, v206
	v_sub_f32_e32 v205, v205, v225
	v_add_f32_e32 v229, v209, v229
	v_exp_f32_e32 v205, v205
	v_sub_f32_e32 v204, v204, v225
	v_add_f32_e32 v229, v208, v229
	v_exp_f32_e32 v204, v204
	v_sub_f32_e32 v203, v203, v225
	v_add_f32_e32 v229, v207, v229
	v_exp_f32_e32 v203, v203
	v_sub_f32_e32 v202, v202, v225
	v_add_f32_e32 v229, v206, v229
	v_exp_f32_e32 v202, v202
	v_sub_f32_e32 v200, v200, v225
	v_add_f32_e32 v229, v205, v229
	v_exp_f32_e32 v230, v200
	v_add_f32_e32 v229, v204, v229
	v_add_f32_e32 v229, v203, v229
	v_add_f32_e32 v229, v202, v229
	v_sub_f32_e32 v199, v199, v225
	v_add_f32_e32 v200, v230, v229
	v_exp_f32_e32 v229, v199
	v_sub_f32_e32 v198, v198, v225
	v_exp_f32_e32 v231, v198
	v_sub_f32_e32 v197, v197, v225
	v_exp_f32_e32 v232, v197
	v_sub_f32_e32 v196, v196, v225
	v_exp_f32_e32 v233, v196
	v_sub_f32_e32 v195, v195, v225
	v_add_f32_e32 v199, v229, v200
	v_exp_f32_e32 v234, v195
	v_sub_f32_e32 v194, v194, v225
	v_add_f32_e32 v198, v231, v199
	v_exp_f32_e32 v235, v194
	v_sub_f32_e32 v193, v193, v225
	v_add_f32_e32 v197, v232, v198
	v_exp_f32_e32 v193, v193
	v_sub_f32_e32 v191, v191, v225
	v_add_f32_e32 v196, v233, v197
	v_exp_f32_e32 v225, v191
	v_add_f32_e32 v195, v234, v196
	v_add_f32_e32 v194, v235, v195
	v_add_f32_e32 v194, v193, v194
	v_add_f32_e32 v191, v225, v194
	v_add_u32_e32 v236, s2, v182
	v_add_f32_e32 v191, v191, v201
	ds_read_b64_tr_b16 v[238:239], v236 offset:18432
	ds_read_b64_tr_b16 v[240:241], v236 offset:19200
	ds_read_b64_tr_b16 v[242:243], v236 offset:18496
	ds_read_b64_tr_b16 v[244:245], v236 offset:19264
	ds_read_b64_tr_b16 v[246:247], v236 offset:21504
	ds_read_b64_tr_b16 v[248:249], v236 offset:22272
	ds_read_b64_tr_b16 v[250:251], v236 offset:21568
	ds_read_b64_tr_b16 v[252:253], v236 offset:22336
	v_cvt_pk_bf16_f32 v194, v224, v223
	v_cvt_pk_bf16_f32 v195, v222, v221
	v_cvt_pk_bf16_f32 v196, v220, v219
	v_cvt_pk_bf16_f32 v197, v218, v217
	s_mov_b64 s[18:19], 0
	s_nop 0
	s_waitcnt lgkmcnt(6)
	v_mfma_f32_32x32x16_bf16 v[2:17], v[238:241], v[194:197], v[2:17]
	ds_read_b64_tr_b16 v[238:239], v236 offset:24576
	ds_read_b64_tr_b16 v[240:241], v236 offset:25344
	s_nop 0
	s_waitcnt lgkmcnt(6)
	v_mfma_f32_32x32x16_bf16 v[18:33], v[242:245], v[194:197], v[18:33]
	ds_read_b64_tr_b16 v[242:243], v236 offset:24640
	ds_read_b64_tr_b16 v[244:245], v236 offset:25408
	v_cvt_pk_bf16_f32 v194, v216, v215
	v_cvt_pk_bf16_f32 v195, v214, v213
	v_cvt_pk_bf16_f32 v196, v212, v211
	v_cvt_pk_bf16_f32 v197, v210, v209
	s_nop 0
	s_nop 0
	s_waitcnt lgkmcnt(6)
	v_mfma_f32_32x32x16_bf16 v[2:17], v[246:249], v[194:197], v[2:17]
	ds_read_b64_tr_b16 v[246:247], v236 offset:27648
	ds_read_b64_tr_b16 v[248:249], v236 offset:28416
	s_nop 0
	s_waitcnt lgkmcnt(6)
	v_mfma_f32_32x32x16_bf16 v[18:33], v[250:253], v[194:197], v[18:33]
	ds_read_b64_tr_b16 v[250:251], v236 offset:27712
	ds_read_b64_tr_b16 v[252:253], v236 offset:28480
	v_cvt_pk_bf16_f32 v194, v208, v207
	v_cvt_pk_bf16_f32 v195, v206, v205
	v_cvt_pk_bf16_f32 v196, v204, v203
	v_cvt_pk_bf16_f32 v197, v202, v230
	s_nop 0
	s_nop 0
	s_waitcnt lgkmcnt(6)
	v_mfma_f32_32x32x16_bf16 v[2:17], v[238:241], v[194:197], v[2:17]
	s_nop 0
	s_waitcnt lgkmcnt(4)
	v_mfma_f32_32x32x16_bf16 v[18:33], v[242:245], v[194:197], v[18:33]
	v_cvt_pk_bf16_f32 v194, v229, v231
	v_cvt_pk_bf16_f32 v195, v232, v233
	v_cvt_pk_bf16_f32 v196, v234, v235
	v_cvt_pk_bf16_f32 v197, v193, v225
	s_nop 0
	s_nop 0
	s_waitcnt lgkmcnt(2)
	v_mfma_f32_32x32x16_bf16 v[2:17], v[246:249], v[194:197], v[2:17]
	s_nop 0
	s_waitcnt lgkmcnt(0)
	v_mfma_f32_32x32x16_bf16 v[18:33], v[250:253], v[194:197], v[18:33]
	v_mov_b32_e32 v188, v191
	v_mov_b32_e32 v189, v0
	s_branch .LBB0_888
.LBB0_883:
	s_waitcnt lgkmcnt(3)
	v_mfma_f32_32x32x16_bf16 v[50:65], v[98:101], v[66:69], 0
	s_nop 3
	ds_read_b128 v[34:37], v192 offset:4608
	ds_read_b128 v[98:101], v192 offset:4640
	s_waitcnt lgkmcnt(1)
	v_mfma_f32_32x32x16_bf16 v[34:49], v[34:37], v[66:69], 0
	v_mfma_f32_32x32x16_bf16 v[50:65], v[102:105], v[70:73], v[50:65]
	s_waitcnt lgkmcnt(0)
	v_mfma_f32_32x32x16_bf16 v[34:49], v[98:101], v[70:73], v[34:49]
	ds_read_b128 v[98:101], v192 offset:4672
	v_mfma_f32_32x32x16_bf16 v[50:65], v[106:109], v[74:77], v[50:65]
	v_mfma_f32_32x32x16_bf16 v[50:65], v[110:113], v[78:81], v[50:65]
	s_waitcnt lgkmcnt(0)
	v_mfma_f32_32x32x16_bf16 v[34:49], v[98:101], v[74:77], v[34:49]
	ds_read_b128 v[98:101], v192 offset:4704
	s_nop 0
	v_cvt_f32_u32_e32 v0, v190
	v_cmp_gt_u32_e32 vcc, s88, v190
	s_and_b64 vcc, s[10:11], vcc
	s_nop 4
	v_fma_f32 v0, -v118, v0, v50
	s_waitcnt lgkmcnt(0)
	v_mfma_f32_32x32x16_bf16 v[34:49], v[98:101], v[78:81], v[34:49]
	v_cndmask_b32_e32 v98, v144, v0, vcc
	v_add_u32_e32 v0, -1, v190
	v_cvt_f32_u32_e32 v0, v0
	v_cmp_lt_i32_e32 vcc, 0, v190
	s_and_b64 vcc, s[10:11], vcc
	v_fma_f32 v0, -v118, v0, v51
	v_add_u32_e32 v51, -2, v190
	v_cndmask_b32_e32 v50, v144, v0, vcc
	v_cmp_gt_u32_e32 vcc, s88, v51
	v_cvt_f32_u32_e32 v51, v51
	s_and_b64 vcc, s[10:11], vcc
	v_max3_f32 v0, v98, s28, v50
	v_fma_f32 v51, -v118, v51, v52
	v_cndmask_b32_e32 v52, v144, v51, vcc
	v_add_u32_e32 v51, -3, v190
	v_cmp_gt_u32_e32 vcc, s88, v51
	v_cvt_f32_u32_e32 v51, v51
	s_and_b64 vcc, s[10:11], vcc
	v_fma_f32 v51, -v118, v51, v53
	v_add_u32_e32 v53, -4, v190
	v_cndmask_b32_e32 v51, v144, v51, vcc
	v_cmp_gt_u32_e32 vcc, s88, v53
	v_cvt_f32_u32_e32 v53, v53
	s_and_b64 vcc, s[10:11], vcc
	v_max3_f32 v0, v0, v52, v51
	v_fma_f32 v53, -v118, v53, v54
	v_add_u32_e32 v54, -5, v190
	v_cndmask_b32_e32 v53, v144, v53, vcc
	v_cmp_gt_u32_e32 vcc, s88, v54
	v_cvt_f32_u32_e32 v54, v54
	s_and_b64 vcc, s[10:11], vcc
	v_fma_f32 v54, -v118, v54, v55
	v_add_u32_e32 v55, -6, v190
	v_cndmask_b32_e32 v54, v144, v54, vcc
	v_cmp_gt_u32_e32 vcc, s88, v55
	v_cvt_f32_u32_e32 v55, v55
	s_and_b64 vcc, s[10:11], vcc
	v_max3_f32 v0, v0, v53, v54
	v_fma_f32 v55, -v118, v55, v56
	v_add_u32_e32 v56, -7, v190
	v_cndmask_b32_e32 v55, v144, v55, vcc
	v_cmp_gt_u32_e32 vcc, s88, v56
	v_cvt_f32_u32_e32 v56, v56
	s_and_b64 vcc, s[10:11], vcc
	v_fma_f32 v56, -v118, v56, v57
	v_add_u32_e32 v57, -16, v190
	v_cndmask_b32_e32 v56, v144, v56, vcc
	v_cmp_gt_u32_e32 vcc, s88, v57
	v_cvt_f32_u32_e32 v57, v57
	s_and_b64 vcc, s[10:11], vcc
	v_max3_f32 v0, v0, v55, v56
	v_fma_f32 v57, -v118, v57, v58
	v_subrev_u32_e32 v58, 17, v190
	v_cndmask_b32_e32 v57, v144, v57, vcc
	v_cmp_gt_u32_e32 vcc, s88, v58
	v_cvt_f32_u32_e32 v58, v58
	s_and_b64 vcc, s[10:11], vcc
	v_fma_f32 v58, -v118, v58, v59
	v_subrev_u32_e32 v59, 18, v190
	v_cndmask_b32_e32 v58, v144, v58, vcc
	v_cmp_gt_u32_e32 vcc, s88, v59
	v_cvt_f32_u32_e32 v59, v59
	s_and_b64 vcc, s[10:11], vcc
	v_max3_f32 v0, v0, v57, v58
	v_fma_f32 v59, -v118, v59, v60
	v_subrev_u32_e32 v60, 19, v190
	v_cndmask_b32_e32 v59, v144, v59, vcc
	v_cmp_gt_u32_e32 vcc, s88, v60
	v_cvt_f32_u32_e32 v60, v60
	s_and_b64 vcc, s[10:11], vcc
	v_fma_f32 v60, -v118, v60, v61
	v_subrev_u32_e32 v61, 20, v190
	v_cndmask_b32_e32 v60, v144, v60, vcc
	v_cmp_gt_u32_e32 vcc, s88, v61
	v_cvt_f32_u32_e32 v61, v61
	s_and_b64 vcc, s[10:11], vcc
	v_max3_f32 v0, v0, v59, v60
	v_fma_f32 v61, -v118, v61, v62
	v_subrev_u32_e32 v62, 21, v190
	v_cndmask_b32_e32 v61, v144, v61, vcc
	v_cmp_gt_u32_e32 vcc, s88, v62
	v_cvt_f32_u32_e32 v62, v62
	s_and_b64 vcc, s[10:11], vcc
	v_fma_f32 v62, -v118, v62, v63
	v_subrev_u32_e32 v63, 22, v190
	v_cndmask_b32_e32 v62, v144, v62, vcc
	v_cmp_gt_u32_e32 vcc, s88, v63
	v_cvt_f32_u32_e32 v63, v63
	s_and_b64 vcc, s[10:11], vcc
	v_max3_f32 v0, v0, v61, v62
	v_fma_f32 v63, -v118, v63, v64
	v_subrev_u32_e32 v64, 23, v190
	v_cndmask_b32_e32 v63, v144, v63, vcc
	v_cmp_gt_u32_e32 vcc, s88, v64
	v_cvt_f32_u32_e32 v64, v64
	s_and_b64 vcc, s[10:11], vcc
	v_fma_f32 v64, -v118, v64, v65
	v_subrev_u32_e32 v65, 32, v190
	v_cndmask_b32_e32 v64, v144, v64, vcc
	v_cmp_gt_u32_e32 vcc, s88, v65
	v_cvt_f32_u32_e32 v65, v65
	s_and_b64 vcc, s[10:11], vcc
	v_max3_f32 v0, v0, v63, v64
	v_fma_f32 v34, -v118, v65, v34
	v_subrev_u32_e32 v65, 33, v190
	v_cndmask_b32_e32 v34, v144, v34, vcc
	v_cmp_gt_u32_e32 vcc, s88, v65
	v_cvt_f32_u32_e32 v65, v65
	s_and_b64 vcc, s[10:11], vcc
	v_fma_f32 v35, -v118, v65, v35
	v_subrev_u32_e32 v65, 34, v190
	v_cndmask_b32_e32 v35, v144, v35, vcc
	v_cmp_gt_u32_e32 vcc, s88, v65
	v_cvt_f32_u32_e32 v65, v65
	s_and_b64 vcc, s[10:11], vcc
	v_max3_f32 v0, v0, v34, v35
	v_fma_f32 v36, -v118, v65, v36
	v_subrev_u32_e32 v65, 35, v190
	v_cndmask_b32_e32 v36, v144, v36, vcc
	v_cmp_gt_u32_e32 vcc, s88, v65
	v_cvt_f32_u32_e32 v65, v65
	s_and_b64 vcc, s[10:11], vcc
	v_fma_f32 v37, -v118, v65, v37
	v_subrev_u32_e32 v65, 36, v190
	v_cndmask_b32_e32 v37, v144, v37, vcc
	v_cmp_gt_u32_e32 vcc, s88, v65
	v_cvt_f32_u32_e32 v65, v65
	s_and_b64 vcc, s[10:11], vcc
	v_max3_f32 v0, v0, v36, v37
	v_fma_f32 v38, -v118, v65, v38
	v_subrev_u32_e32 v65, 37, v190
	v_cndmask_b32_e32 v38, v144, v38, vcc
	v_cmp_gt_u32_e32 vcc, s88, v65
	v_cvt_f32_u32_e32 v65, v65
	s_and_b64 vcc, s[10:11], vcc
	v_fma_f32 v39, -v118, v65, v39
	v_subrev_u32_e32 v65, 38, v190
	v_cndmask_b32_e32 v39, v144, v39, vcc
	v_cmp_gt_u32_e32 vcc, s88, v65
	v_cvt_f32_u32_e32 v65, v65
	s_and_b64 vcc, s[10:11], vcc
	v_max3_f32 v0, v0, v38, v39
	v_fma_f32 v40, -v118, v65, v40
	v_subrev_u32_e32 v65, 39, v190
	v_cndmask_b32_e32 v40, v144, v40, vcc
	v_cmp_gt_u32_e32 vcc, s88, v65
	v_cvt_f32_u32_e32 v65, v65
	s_and_b64 vcc, s[10:11], vcc
	v_fma_f32 v41, -v118, v65, v41
	v_subrev_u32_e32 v65, 48, v190
	v_cndmask_b32_e32 v41, v144, v41, vcc
	v_cmp_gt_u32_e32 vcc, s88, v65
	v_cvt_f32_u32_e32 v65, v65
	s_and_b64 vcc, s[10:11], vcc
	v_max3_f32 v0, v0, v40, v41
	v_fma_f32 v42, -v118, v65, v42
	v_subrev_u32_e32 v65, 49, v190
	v_cndmask_b32_e32 v42, v144, v42, vcc
	v_cmp_gt_u32_e32 vcc, s88, v65
	v_cvt_f32_u32_e32 v65, v65
	s_and_b64 vcc, s[10:11], vcc
	v_fma_f32 v43, -v118, v65, v43
	v_subrev_u32_e32 v65, 50, v190
	v_cndmask_b32_e32 v43, v144, v43, vcc
	v_cmp_gt_u32_e32 vcc, s88, v65
	v_cvt_f32_u32_e32 v65, v65
	s_and_b64 vcc, s[10:11], vcc
	v_max3_f32 v0, v0, v42, v43
	v_fma_f32 v44, -v118, v65, v44
	v_subrev_u32_e32 v65, 51, v190
	v_cndmask_b32_e32 v44, v144, v44, vcc
	v_cmp_gt_u32_e32 vcc, s88, v65
	v_cvt_f32_u32_e32 v65, v65
	s_and_b64 vcc, s[10:11], vcc
	v_fma_f32 v45, -v118, v65, v45
	v_subrev_u32_e32 v65, 52, v190
	v_cndmask_b32_e32 v45, v144, v45, vcc
	v_cmp_gt_u32_e32 vcc, s88, v65
	v_cvt_f32_u32_e32 v65, v65
	s_and_b64 vcc, s[10:11], vcc
	v_max3_f32 v0, v0, v44, v45
	v_fma_f32 v46, -v118, v65, v46
	v_subrev_u32_e32 v65, 53, v190
	v_cndmask_b32_e32 v46, v144, v46, vcc
	v_cmp_gt_u32_e32 vcc, s88, v65
	v_cvt_f32_u32_e32 v65, v65
	s_and_b64 vcc, s[10:11], vcc
	v_fma_f32 v47, -v118, v65, v47
	v_subrev_u32_e32 v65, 54, v190
	v_cndmask_b32_e32 v47, v144, v47, vcc
	v_cmp_gt_u32_e32 vcc, s88, v65
	v_cvt_f32_u32_e32 v65, v65
	s_and_b64 vcc, s[10:11], vcc
	v_max3_f32 v0, v0, v46, v47
	v_fma_f32 v48, -v118, v65, v48
	v_cndmask_b32_e32 v65, v144, v48, vcc
	v_subrev_u32_e32 v48, 55, v190
	v_cmp_gt_u32_e32 vcc, s88, v48
	v_cvt_f32_u32_e32 v48, v48
	s_and_b64 vcc, s[10:11], vcc
	v_fma_f32 v48, -v118, v48, v49
	v_cndmask_b32_e32 v99, v144, v48, vcc
	v_max3_f32 v0, v0, v65, v99
	ds_bpermute_b32 v48, v186, v0
	s_waitcnt lgkmcnt(0)
	v_max3_f32 v0, v189, v0, v48
	v_cmp_gt_f32_e32 vcc, v0, v189
	s_cbranch_vccz .LBB0_886
	v_sub_f32_e32 v48, v189, v0
	v_exp_f32_e32 v48, v48
	s_nop 0
	v_mul_f32_e32 v188, v188, v48
	v_pk_mul_f32 v[32:33], v[32:33], v[48:49] op_sel_hi:[1,0]
	v_pk_mul_f32 v[30:31], v[30:31], v[48:49] op_sel_hi:[1,0]
	v_pk_mul_f32 v[28:29], v[28:29], v[48:49] op_sel_hi:[1,0]
	v_pk_mul_f32 v[26:27], v[26:27], v[48:49] op_sel_hi:[1,0]
	v_pk_mul_f32 v[24:25], v[24:25], v[48:49] op_sel_hi:[1,0]
	v_pk_mul_f32 v[22:23], v[22:23], v[48:49] op_sel_hi:[1,0]
	v_pk_mul_f32 v[20:21], v[20:21], v[48:49] op_sel_hi:[1,0]
	v_pk_mul_f32 v[18:19], v[18:19], v[48:49] op_sel_hi:[1,0]
	v_pk_mul_f32 v[16:17], v[16:17], v[48:49] op_sel_hi:[1,0]
	v_pk_mul_f32 v[14:15], v[14:15], v[48:49] op_sel_hi:[1,0]
	v_pk_mul_f32 v[12:13], v[12:13], v[48:49] op_sel_hi:[1,0]
	v_pk_mul_f32 v[10:11], v[10:11], v[48:49] op_sel_hi:[1,0]
	v_pk_mul_f32 v[8:9], v[8:9], v[48:49] op_sel_hi:[1,0]
	v_pk_mul_f32 v[6:7], v[6:7], v[48:49] op_sel_hi:[1,0]
	v_pk_mul_f32 v[4:5], v[4:5], v[48:49] op_sel_hi:[1,0]
	v_pk_mul_f32 v[2:3], v[2:3], v[48:49] op_sel_hi:[1,0]
.LBB0_886:
	v_sub_f32_e32 v48, v98, v0
	v_exp_f32_e32 v48, v48
	v_cmp_lt_f32_e32 vcc, s29, v98
	v_sub_f32_e32 v49, v50, v0
	v_exp_f32_e32 v49, v49
	v_cndmask_b32_e32 v48, 0, v48, vcc
	v_cmp_lt_f32_e32 vcc, s29, v50
	v_sub_f32_e32 v50, v52, v0
	v_exp_f32_e32 v50, v50
	v_cndmask_b32_e32 v49, 0, v49, vcc
	v_cmp_lt_f32_e32 vcc, s29, v52
	v_add_f32_e32 v98, 0, v48
	v_add_f32_e32 v98, v49, v98
	v_cndmask_b32_e32 v50, 0, v50, vcc
	v_cmp_lt_f32_e32 vcc, s29, v51
	v_sub_f32_e32 v51, v51, v0
	v_exp_f32_e32 v51, v51
	v_add_f32_e32 v52, v50, v98
	v_add_u32_e32 v106, s2, v182
	v_cndmask_b32_e32 v51, 0, v51, vcc
	v_add_f32_e32 v98, v51, v52
	v_sub_f32_e32 v52, v53, v0
	v_exp_f32_e32 v52, v52
	v_cmp_lt_f32_e32 vcc, s29, v53
	s_nop 1
	v_cndmask_b32_e32 v52, 0, v52, vcc
	v_cmp_lt_f32_e32 vcc, s29, v54
	v_sub_f32_e32 v54, v54, v0
	v_exp_f32_e32 v54, v54
	v_add_f32_e32 v53, v52, v98
	v_cndmask_b32_e32 v54, 0, v54, vcc
	v_cmp_lt_f32_e32 vcc, s29, v55
	v_sub_f32_e32 v55, v55, v0
	v_exp_f32_e32 v55, v55
	v_add_f32_e32 v53, v54, v53
	v_cndmask_b32_e32 v98, 0, v55, vcc
	v_sub_f32_e32 v55, v56, v0
	v_exp_f32_e32 v55, v55
	v_cmp_lt_f32_e32 vcc, s29, v56
	v_add_f32_e32 v53, v98, v53
	s_nop 0
	v_cndmask_b32_e32 v100, 0, v55, vcc
	v_add_f32_e32 v55, v100, v53
	v_sub_f32_e32 v53, v57, v0
	v_exp_f32_e32 v53, v53
	v_cmp_lt_f32_e32 vcc, s29, v57
	s_nop 1
	v_cndmask_b32_e32 v53, 0, v53, vcc
	v_add_f32_e32 v56, v53, v55
	v_sub_f32_e32 v55, v58, v0
	v_exp_f32_e32 v55, v55
	v_cmp_lt_f32_e32 vcc, s29, v58
	s_nop 1
	v_cndmask_b32_e32 v55, 0, v55, vcc
	v_add_f32_e32 v57, v55, v56
	v_sub_f32_e32 v56, v59, v0
	v_exp_f32_e32 v56, v56
	v_cmp_lt_f32_e32 vcc, s29, v59
	s_nop 1
	v_cndmask_b32_e32 v56, 0, v56, vcc
	v_add_f32_e32 v58, v56, v57
	v_sub_f32_e32 v57, v60, v0
	v_exp_f32_e32 v57, v57
	v_cmp_lt_f32_e32 vcc, s29, v60
	v_sub_f32_e32 v60, v62, v0
	v_exp_f32_e32 v60, v60
	v_cndmask_b32_e32 v57, 0, v57, vcc
	v_add_f32_e32 v59, v57, v58
	v_sub_f32_e32 v58, v61, v0
	v_exp_f32_e32 v58, v58
	v_cmp_lt_f32_e32 vcc, s29, v61
	v_sub_f32_e32 v61, v63, v0
	v_exp_f32_e32 v61, v61
	v_cndmask_b32_e32 v58, 0, v58, vcc
	v_cmp_lt_f32_e32 vcc, s29, v62
	v_sub_f32_e32 v62, v64, v0
	v_exp_f32_e32 v62, v62
	v_cndmask_b32_e32 v60, 0, v60, vcc
	v_cmp_lt_f32_e32 vcc, s29, v63
	v_add_f32_e32 v59, v58, v59
	v_add_f32_e32 v59, v60, v59
	v_cndmask_b32_e32 v61, 0, v61, vcc
	v_cmp_lt_f32_e32 vcc, s29, v64
	v_add_f32_e32 v59, v61, v59
	s_nop 0
	v_cndmask_b32_e32 v62, 0, v62, vcc
	v_cmp_lt_f32_e32 vcc, s29, v34
	v_sub_f32_e32 v34, v34, v0
	v_exp_f32_e32 v34, v34
	v_add_f32_e32 v59, v62, v59
	v_cndmask_b32_e32 v34, 0, v34, vcc
	v_cmp_lt_f32_e32 vcc, s29, v35
	v_sub_f32_e32 v35, v35, v0
	v_exp_f32_e32 v35, v35
	v_add_f32_e32 v59, v34, v59
	v_cndmask_b32_e32 v35, 0, v35, vcc
	v_cmp_lt_f32_e32 vcc, s29, v36
	v_sub_f32_e32 v36, v36, v0
	v_exp_f32_e32 v36, v36
	v_add_f32_e32 v59, v35, v59
	v_cndmask_b32_e32 v36, 0, v36, vcc
	v_cmp_lt_f32_e32 vcc, s29, v37
	v_sub_f32_e32 v37, v37, v0
	v_exp_f32_e32 v37, v37
	v_add_f32_e32 v59, v36, v59
	v_cndmask_b32_e32 v63, 0, v37, vcc
	v_cmp_lt_f32_e32 vcc, s29, v38
	v_sub_f32_e32 v38, v38, v0
	v_exp_f32_e32 v38, v38
	v_add_f32_e32 v37, v63, v59
	v_cndmask_b32_e32 v59, 0, v38, vcc
	v_sub_f32_e32 v38, v39, v0
	v_exp_f32_e32 v38, v38
	v_cmp_lt_f32_e32 vcc, s29, v39
	v_add_f32_e32 v37, v59, v37
	v_sub_f32_e32 v39, v43, v0
	v_cndmask_b32_e32 v64, 0, v38, vcc
	v_sub_f32_e32 v38, v40, v0
	v_exp_f32_e32 v38, v38
	v_cmp_lt_f32_e32 vcc, s29, v40
	v_add_f32_e32 v37, v64, v37
	v_exp_f32_e32 v39, v39
	v_cndmask_b32_e32 v101, 0, v38, vcc
	v_sub_f32_e32 v38, v41, v0
	v_exp_f32_e32 v38, v38
	v_cmp_lt_f32_e32 vcc, s29, v41
	v_add_f32_e32 v37, v101, v37
	v_cvt_pk_bf16_f32 v40, v52, v54
	v_cndmask_b32_e32 v102, 0, v38, vcc
	v_add_f32_e32 v38, v102, v37
	v_sub_f32_e32 v37, v42, v0
	v_exp_f32_e32 v37, v37
	v_cmp_lt_f32_e32 vcc, s29, v42
	v_cvt_pk_bf16_f32 v41, v98, v100
	s_nop 0
	v_cndmask_b32_e32 v37, 0, v37, vcc
	v_cmp_lt_f32_e32 vcc, s29, v43
	v_add_f32_e32 v38, v37, v38
	s_nop 0
	v_cndmask_b32_e32 v103, 0, v39, vcc
	v_sub_f32_e32 v39, v44, v0
	v_exp_f32_e32 v39, v39
	v_cmp_lt_f32_e32 vcc, s29, v44
	v_add_f32_e32 v38, v103, v38
	s_nop 0
	v_cndmask_b32_e32 v104, 0, v39, vcc
	v_sub_f32_e32 v39, v45, v0
	v_exp_f32_e32 v39, v39
	v_cmp_lt_f32_e32 vcc, s29, v45
	v_add_f32_e32 v38, v104, v38
	ds_read_b64_tr_b16 v[238:239], v106 offset:18432
	ds_read_b64_tr_b16 v[240:241], v106 offset:19200
	ds_read_b64_tr_b16 v[242:243], v106 offset:18496
	ds_read_b64_tr_b16 v[244:245], v106 offset:19264
	ds_read_b64_tr_b16 v[246:247], v106 offset:21504
	ds_read_b64_tr_b16 v[248:249], v106 offset:22272
	ds_read_b64_tr_b16 v[250:251], v106 offset:21568
	ds_read_b64_tr_b16 v[252:253], v106 offset:22336
	v_cndmask_b32_e32 v105, 0, v39, vcc
	v_sub_f32_e32 v39, v46, v0
	v_exp_f32_e32 v39, v39
	v_cmp_lt_f32_e32 vcc, s29, v46
	v_add_f32_e32 v38, v105, v38
	s_nop 0
	v_cndmask_b32_e32 v46, 0, v39, vcc
	v_sub_f32_e32 v39, v47, v0
	v_exp_f32_e32 v39, v39
	v_cmp_lt_f32_e32 vcc, s29, v47
	v_add_f32_e32 v38, v46, v38
	s_nop 0
	v_cndmask_b32_e32 v47, 0, v39, vcc
	v_sub_f32_e32 v39, v65, v0
	v_exp_f32_e32 v39, v39
	v_cmp_lt_f32_e32 vcc, s29, v65
	v_add_f32_e32 v38, v47, v38
	s_nop 0
	v_cndmask_b32_e32 v65, 0, v39, vcc
	v_sub_f32_e32 v39, v99, v0
	v_exp_f32_e32 v39, v39
	v_cmp_lt_f32_e32 vcc, s29, v99
	v_add_f32_e32 v38, v65, v38
	s_nop 0
	v_cndmask_b32_e32 v99, 0, v39, vcc
	v_add_f32_e32 v38, v99, v38
	v_add_f32_e32 v191, v38, v188
	v_cvt_pk_bf16_f32 v38, v48, v49
	v_cvt_pk_bf16_f32 v39, v50, v51
	s_nop 0
	s_nop 0
	s_waitcnt lgkmcnt(6)
	v_mfma_f32_32x32x16_bf16 v[2:17], v[238:241], v[38:41], v[2:17]
	ds_read_b64_tr_b16 v[238:239], v106 offset:24576
	ds_read_b64_tr_b16 v[240:241], v106 offset:25344
	s_nop 0
	s_waitcnt lgkmcnt(6)
	v_mfma_f32_32x32x16_bf16 v[18:33], v[242:245], v[38:41], v[18:33]
	ds_read_b64_tr_b16 v[242:243], v106 offset:24640
	ds_read_b64_tr_b16 v[244:245], v106 offset:25408
	v_cvt_pk_bf16_f32 v38, v53, v55
	v_cvt_pk_bf16_f32 v39, v56, v57
	v_cvt_pk_bf16_f32 v40, v58, v60
	v_cvt_pk_bf16_f32 v41, v61, v62
	s_nop 0
	s_nop 0
	s_waitcnt lgkmcnt(6)
	v_mfma_f32_32x32x16_bf16 v[2:17], v[246:249], v[38:41], v[2:17]
	ds_read_b64_tr_b16 v[246:247], v106 offset:27648
	ds_read_b64_tr_b16 v[248:249], v106 offset:28416
	s_nop 0
	s_waitcnt lgkmcnt(6)
	v_mfma_f32_32x32x16_bf16 v[18:33], v[250:253], v[38:41], v[18:33]
	ds_read_b64_tr_b16 v[250:251], v106 offset:27712
	ds_read_b64_tr_b16 v[252:253], v106 offset:28480
	v_cvt_pk_bf16_f32 v38, v34, v35
	v_cvt_pk_bf16_f32 v39, v36, v63
	v_cvt_pk_bf16_f32 v40, v59, v64
	v_cvt_pk_bf16_f32 v41, v101, v102
	v_cvt_pk_bf16_f32 v34, v37, v103
	v_cvt_pk_bf16_f32 v35, v104, v105
	s_nop 0
	s_waitcnt lgkmcnt(6)
	v_mfma_f32_32x32x16_bf16 v[2:17], v[238:241], v[38:41], v[2:17]
	v_cvt_pk_bf16_f32 v36, v46, v47
	v_cvt_pk_bf16_f32 v37, v65, v99
	s_nop 0
	s_waitcnt lgkmcnt(4)
	v_mfma_f32_32x32x16_bf16 v[18:33], v[242:245], v[38:41], v[18:33]
	s_nop 0
	s_waitcnt lgkmcnt(2)
	v_mfma_f32_32x32x16_bf16 v[2:17], v[246:249], v[34:37], v[2:17]
	s_nop 0
	s_waitcnt lgkmcnt(0)
	v_mfma_f32_32x32x16_bf16 v[18:33], v[250:253], v[34:37], v[18:33]
	v_mov_b32_e32 v188, v191
	v_mov_b32_e32 v189, v0

.LBB0_930:
	s_or_b64 exec, exec, s[16:17]
	s_mul_i32 s16, s3, 0x3000
	v_add_u32_e32 v139, s16, v123
	ds_read_b64_tr_b16 v[238:239], v139 offset:18432
	ds_read_b64_tr_b16 v[240:241], v139 offset:19200
	ds_read_b64_tr_b16 v[242:243], v139 offset:18496
	ds_read_b64_tr_b16 v[244:245], v139 offset:19264
	ds_read_b64_tr_b16 v[246:247], v139 offset:21504
	ds_read_b64_tr_b16 v[248:249], v139 offset:22272
	ds_read_b64_tr_b16 v[250:251], v139 offset:21568
	ds_read_b64_tr_b16 v[252:253], v139 offset:22336
	v_cvt_pk_bf16_f32 v182, v34, v35
	v_cvt_pk_bf16_f32 v183, v36, v39
	v_cvt_pk_bf16_f32 v184, v40, v43
	v_cvt_pk_bf16_f32 v185, v44, v48
	v_mov_b64_e32 v[48:49], v[16:17]
	v_mov_b64_e32 v[46:47], v[14:15]
	v_mov_b64_e32 v[44:45], v[12:13]
	v_mov_b64_e32 v[42:43], v[10:11]
	v_mov_b64_e32 v[40:41], v[8:9]
	v_mov_b64_e32 v[38:39], v[6:7]
	v_mov_b64_e32 v[36:37], v[4:5]
	v_mov_b64_e32 v[34:35], v[2:3]
	s_mov_b64 s[16:17], 0
	s_nop 0
	s_waitcnt lgkmcnt(6)
	v_mfma_f32_32x32x16_bf16 v[34:49], v[238:241], v[182:185], v[34:49]
	ds_read_b64_tr_b16 v[238:239], v139 offset:24576
	ds_read_b64_tr_b16 v[240:241], v139 offset:25344
	v_mov_b64_e32 v[64:65], v[32:33]
	v_mov_b64_e32 v[62:63], v[30:31]
	v_mov_b64_e32 v[60:61], v[28:29]
	v_mov_b64_e32 v[58:59], v[26:27]
	v_mov_b64_e32 v[56:57], v[24:25]
	v_mov_b64_e32 v[54:55], v[22:23]
	v_mov_b64_e32 v[52:53], v[20:21]
	v_mov_b64_e32 v[50:51], v[18:19]
	s_nop 0
	s_nop 0
	s_waitcnt lgkmcnt(6)
	v_mfma_f32_32x32x16_bf16 v[50:65], v[242:245], v[182:185], v[50:65]
	ds_read_b64_tr_b16 v[242:243], v139 offset:24640
	ds_read_b64_tr_b16 v[244:245], v139 offset:25408
	v_cvt_pk_bf16_f32 v182, v96, v97
	v_cvt_pk_bf16_f32 v183, v111, v114
	v_cvt_pk_bf16_f32 v184, v115, v128
	v_cvt_pk_bf16_f32 v185, v129, v130
	v_cvt_pk_bf16_f32 v97, v99, v131
	v_cvt_pk_bf16_f32 v96, v127, v98
	s_nop 0
	s_waitcnt lgkmcnt(6)
	v_mfma_f32_32x32x16_bf16 v[34:49], v[246:249], v[182:185], v[34:49]
	ds_read_b64_tr_b16 v[246:247], v139 offset:27648
	ds_read_b64_tr_b16 v[248:249], v139 offset:28416
	v_cvt_pk_bf16_f32 v98, v132, v133
	v_cvt_pk_bf16_f32 v99, v110, v134
	s_nop 0
	s_waitcnt lgkmcnt(6)
	v_mfma_f32_32x32x16_bf16 v[50:65], v[250:253], v[182:185], v[50:65]
	ds_read_b64_tr_b16 v[250:251], v139 offset:27712
	ds_read_b64_tr_b16 v[252:253], v139 offset:28480
	s_nop 0
	s_waitcnt lgkmcnt(6)
	v_mfma_f32_32x32x16_bf16 v[34:49], v[238:241], v[96:99], v[34:49]
	s_nop 0
	s_waitcnt lgkmcnt(4)
	v_mfma_f32_32x32x16_bf16 v[50:65], v[242:245], v[96:99], v[50:65]
	v_cvt_pk_bf16_f32 v96, v109, v112
	v_cvt_pk_bf16_f32 v97, v113, v135
	v_cvt_pk_bf16_f32 v98, v136, v137
	v_cvt_pk_bf16_f32 v99, v126, v138
	s_nop 0
	s_nop 0
	s_waitcnt lgkmcnt(2)
	v_mfma_f32_32x32x16_bf16 v[34:49], v[246:249], v[96:99], v[34:49]
	s_nop 0
	s_waitcnt lgkmcnt(0)
	v_mfma_f32_32x32x16_bf16 v[50:65], v[250:253], v[96:99], v[50:65]

.LBB0_953:
	s_or_b64 exec, exec, s[16:17]
	ds_read_b64_tr_b16 v[238:239], v123 offset:30720
	ds_read_b64_tr_b16 v[240:241], v123 offset:31488
	ds_read_b64_tr_b16 v[242:243], v123 offset:30784
	ds_read_b64_tr_b16 v[244:245], v123 offset:31552
	ds_read_b64_tr_b16 v[246:247], v123 offset:33792
	ds_read_b64_tr_b16 v[248:249], v123 offset:34560
	ds_read_b64_tr_b16 v[250:251], v123 offset:33856
	ds_read_b64_tr_b16 v[252:253], v123 offset:34624
	v_cvt_pk_bf16_f32 v112, v0, v34
	v_cvt_pk_bf16_f32 v113, v35, v39
	v_cvt_pk_bf16_f32 v114, v40, v43
	v_cvt_pk_bf16_f32 v115, v44, v48
	v_cvt_pk_bf16_f32 v38, v38, v41
	v_cvt_pk_bf16_f32 v39, v42, v46
	s_nop 0
	s_waitcnt lgkmcnt(6)
	v_mfma_f32_32x32x16_bf16 v[2:17], v[238:241], v[112:115], v[2:17]
	ds_read_b64_tr_b16 v[238:239], v123 offset:36864
	ds_read_b64_tr_b16 v[240:241], v123 offset:37632
	v_cvt_pk_bf16_f32 v40, v47, v50
	v_cvt_pk_bf16_f32 v41, v51, v53
	v_cvt_pk_bf16_f32 v34, v49, v52
	v_cvt_pk_bf16_f32 v35, v36, v37
	v_cvt_pk_bf16_f32 v36, v54, v56
	v_cvt_pk_bf16_f32 v37, v57, v60
	s_nop 0
	s_waitcnt lgkmcnt(6)
	v_mfma_f32_32x32x16_bf16 v[18:33], v[242:245], v[112:115], v[18:33]
	ds_read_b64_tr_b16 v[242:243], v123 offset:36928
	ds_read_b64_tr_b16 v[244:245], v123 offset:37696
	v_cmp_gt_i32_e64 s[14:15], s95, v109
	s_nop 1
	v_cndmask_b32_e64 v0, 0, 1, s[14:15]
	v_cndmask_b32_e64 v0, v0, 2, vcc
	v_cmp_lt_i32_e32 vcc, 1, v0
	s_nop 0
	s_waitcnt lgkmcnt(6)
	v_mfma_f32_32x32x16_bf16 v[2:17], v[246:249], v[38:41], v[2:17]
	ds_read_b64_tr_b16 v[246:247], v123 offset:39936
	ds_read_b64_tr_b16 v[248:249], v123 offset:40704
	s_nop 0
	s_waitcnt lgkmcnt(6)
	v_mfma_f32_32x32x16_bf16 v[18:33], v[250:253], v[38:41], v[18:33]
	ds_read_b64_tr_b16 v[250:251], v123 offset:40000
	ds_read_b64_tr_b16 v[252:253], v123 offset:40768
	s_nop 0
	s_waitcnt lgkmcnt(6)
	v_mfma_f32_32x32x16_bf16 v[2:17], v[238:241], v[34:37], v[2:17]
	s_nop 0
	s_waitcnt lgkmcnt(4)
	v_mfma_f32_32x32x16_bf16 v[18:33], v[242:245], v[34:37], v[18:33]
	v_cvt_pk_bf16_f32 v34, v55, v58
	v_cvt_pk_bf16_f32 v35, v59, v45
	v_cvt_pk_bf16_f32 v36, v61, v62
	v_cvt_pk_bf16_f32 v37, v63, v64
	s_nop 0
	s_nop 0
	s_waitcnt lgkmcnt(2)
	v_mfma_f32_32x32x16_bf16 v[2:17], v[246:249], v[34:37], v[2:17]
	s_nop 0
	s_waitcnt lgkmcnt(0)
	v_mfma_f32_32x32x16_bf16 v[18:33], v[250:253], v[34:37], v[18:33]
	v_mov_b32_e32 v38, v165
	s_and_saveexec_b64 s[2:3], vcc
	s_xor_b64 s[14:15], exec, s[2:3]
	v_cvt_pk_bf16_f32 v37, v90, v91
	v_cvt_pk_bf16_f32 v36, v88, v89
	v_cvt_pk_bf16_f32 v35, v86, v87
	v_cvt_pk_bf16_f32 v34, v84, v85
	s_andn2_saveexec_b64 s[14:15], s[14:15]
	s_cbranch_execz .LBB0_959
	v_cmp_eq_u32_e32 vcc, 1, v0
	v_mov_b32_e32 v37, 0
	v_mov_b32_e32 v36, 0
	v_mov_b32_e32 v35, 0
	v_mov_b32_e32 v34, 0
	s_and_saveexec_b64 s[16:17], vcc
	v_mov_b32_e32 v37, v87
	v_mov_b32_e32 v36, v86
	v_mov_b32_e32 v35, v85
	v_mov_b32_e32 v34, v84
	s_or_b64 exec, exec, s[16:17]

.LBB0_1028:
	v_mul_f32_e64 v209, -v118, v209
	v_sub_f32_e32 v209, v0, v209
	v_cndmask_b32_e64 v209, v146, v209, s[10:11]
	v_sub_f32_e32 v208, v208, v209
	v_exp_f32_e32 v208, v208
	v_sub_f32_e32 v207, v207, v209
	v_exp_f32_e32 v207, v207
	v_sub_f32_e32 v206, v206, v209
	v_exp_f32_e32 v206, v206
	v_sub_f32_e32 v205, v205, v209
	v_exp_f32_e32 v205, v205
	v_sub_f32_e32 v204, v204, v209
	v_add_f32_e32 v210, 0, v208
	v_exp_f32_e32 v204, v204
	v_sub_f32_e32 v203, v203, v209
	v_add_f32_e32 v210, v207, v210
	v_exp_f32_e32 v203, v203
	v_sub_f32_e32 v202, v202, v209
	v_add_f32_e32 v210, v206, v210
	v_exp_f32_e32 v202, v202
	v_sub_f32_e32 v201, v201, v209
	v_add_f32_e32 v210, v205, v210
	v_exp_f32_e32 v201, v201
	v_sub_f32_e32 v200, v200, v209
	v_add_f32_e32 v210, v204, v210
	v_exp_f32_e32 v200, v200
	v_sub_f32_e32 v199, v199, v209
	v_add_f32_e32 v210, v203, v210
	v_exp_f32_e32 v199, v199
	v_sub_f32_e32 v198, v198, v209
	v_add_f32_e32 v210, v202, v210
	v_exp_f32_e32 v198, v198
	v_sub_f32_e32 v197, v197, v209
	v_add_f32_e32 v210, v201, v210
	v_exp_f32_e32 v197, v197
	v_sub_f32_e32 v196, v196, v209
	v_add_f32_e32 v210, v200, v210
	v_exp_f32_e32 v196, v196
	v_sub_f32_e32 v195, v195, v209
	v_add_f32_e32 v210, v199, v210
	v_exp_f32_e32 v195, v195
	v_sub_f32_e32 v194, v194, v209
	v_add_f32_e32 v210, v198, v210
	v_exp_f32_e32 v194, v194
	v_sub_f32_e32 v193, v193, v209
	v_add_f32_e32 v210, v197, v210
	v_exp_f32_e32 v193, v193
	v_sub_f32_e32 v192, v192, v209
	v_add_f32_e32 v210, v196, v210
	v_exp_f32_e32 v192, v192
	v_sub_f32_e32 v191, v191, v209
	v_add_f32_e32 v210, v195, v210
	v_exp_f32_e32 v191, v191
	v_sub_f32_e32 v190, v190, v209
	v_add_f32_e32 v210, v194, v210
	v_exp_f32_e32 v190, v190
	v_sub_f32_e32 v189, v189, v209
	v_add_f32_e32 v210, v193, v210
	v_exp_f32_e32 v189, v189
	v_sub_f32_e32 v188, v188, v209
	v_add_f32_e32 v210, v192, v210
	v_exp_f32_e32 v188, v188
	v_sub_f32_e32 v187, v187, v209
	v_add_f32_e32 v210, v191, v210
	v_exp_f32_e32 v187, v187
	v_sub_f32_e32 v185, v185, v209
	v_add_f32_e32 v210, v190, v210
	v_exp_f32_e32 v211, v185
	v_add_f32_e32 v210, v189, v210
	v_add_f32_e32 v210, v188, v210
	v_add_f32_e32 v210, v187, v210
	v_sub_f32_e32 v184, v184, v209
	v_add_f32_e32 v185, v211, v210
	v_exp_f32_e32 v210, v184
	v_sub_f32_e32 v183, v183, v209
	v_exp_f32_e32 v212, v183
	v_sub_f32_e32 v182, v182, v209
	v_exp_f32_e32 v213, v182
	v_sub_f32_e32 v181, v181, v209
	v_exp_f32_e32 v181, v181
	v_sub_f32_e32 v139, v139, v209
	v_add_f32_e32 v184, v210, v185
	v_exp_f32_e32 v214, v139
	v_sub_f32_e32 v138, v138, v209
	v_add_f32_e32 v183, v212, v184
	v_exp_f32_e32 v215, v138
	v_sub_f32_e32 v137, v137, v209
	v_add_f32_e32 v182, v213, v183
	v_exp_f32_e32 v216, v137
	v_sub_f32_e32 v136, v136, v209
	v_add_f32_e32 v182, v181, v182
	v_exp_f32_e32 v217, v136
	v_sub_f32_e32 v134, v134, v209
	v_add_f32_e32 v139, v214, v182
	v_exp_f32_e32 v209, v134
	v_add_f32_e32 v138, v215, v139
	v_add_f32_e32 v137, v216, v138
	v_add_f32_e32 v136, v217, v137
	v_add_f32_e32 v134, v209, v136
	v_add_f32_e32 v134, v134, v186
	v_add_u32_e32 v186, s66, v123
	ds_read_b64_tr_b16 v[238:239], v186 offset:18432
	ds_read_b64_tr_b16 v[240:241], v186 offset:19200
	ds_read_b64_tr_b16 v[242:243], v186 offset:18496
	ds_read_b64_tr_b16 v[244:245], v186 offset:19264
	ds_read_b64_tr_b16 v[246:247], v186 offset:21504
	ds_read_b64_tr_b16 v[248:249], v186 offset:22272
	ds_read_b64_tr_b16 v[250:251], v186 offset:21568
	ds_read_b64_tr_b16 v[252:253], v186 offset:22336
	v_cvt_pk_bf16_f32 v136, v208, v207
	v_cvt_pk_bf16_f32 v137, v206, v205
	v_cvt_pk_bf16_f32 v138, v204, v203
	v_cvt_pk_bf16_f32 v139, v202, v201
	s_mov_b64 s[12:13], 0
	s_nop 0
	s_waitcnt lgkmcnt(6)
	v_mfma_f32_32x32x16_bf16 v[34:49], v[238:241], v[136:139], v[34:49]
	ds_read_b64_tr_b16 v[238:239], v186 offset:24576
	ds_read_b64_tr_b16 v[240:241], v186 offset:25344
	s_nop 0
	s_waitcnt lgkmcnt(6)
	v_mfma_f32_32x32x16_bf16 v[50:65], v[242:245], v[136:139], v[50:65]
	ds_read_b64_tr_b16 v[242:243], v186 offset:24640
	ds_read_b64_tr_b16 v[244:245], v186 offset:25408
	v_cvt_pk_bf16_f32 v136, v200, v199
	v_cvt_pk_bf16_f32 v137, v198, v197
	v_cvt_pk_bf16_f32 v138, v196, v195
	v_cvt_pk_bf16_f32 v139, v194, v193
	s_nop 0
	s_nop 0
	s_waitcnt lgkmcnt(6)
	v_mfma_f32_32x32x16_bf16 v[34:49], v[246:249], v[136:139], v[34:49]
	ds_read_b64_tr_b16 v[246:247], v186 offset:27648
	ds_read_b64_tr_b16 v[248:249], v186 offset:28416
	s_nop 0
	s_waitcnt lgkmcnt(6)
	v_mfma_f32_32x32x16_bf16 v[50:65], v[250:253], v[136:139], v[50:65]
	ds_read_b64_tr_b16 v[250:251], v186 offset:27712
	ds_read_b64_tr_b16 v[252:253], v186 offset:28480
	v_cvt_pk_bf16_f32 v136, v192, v191
	v_cvt_pk_bf16_f32 v137, v190, v189
	v_cvt_pk_bf16_f32 v138, v188, v187
	v_cvt_pk_bf16_f32 v139, v211, v210
	s_nop 0
	s_nop 0
	s_waitcnt lgkmcnt(6)
	v_mfma_f32_32x32x16_bf16 v[34:49], v[238:241], v[136:139], v[34:49]
	s_nop 0
	s_waitcnt lgkmcnt(4)
	v_mfma_f32_32x32x16_bf16 v[50:65], v[242:245], v[136:139], v[50:65]
	v_cvt_pk_bf16_f32 v136, v212, v213
	v_cvt_pk_bf16_f32 v137, v181, v214
	v_cvt_pk_bf16_f32 v138, v215, v216
	v_cvt_pk_bf16_f32 v139, v217, v209
	s_nop 0
	s_nop 0
	s_waitcnt lgkmcnt(2)
	v_mfma_f32_32x32x16_bf16 v[34:49], v[246:249], v[136:139], v[34:49]
	s_nop 0
	s_waitcnt lgkmcnt(0)
	v_mfma_f32_32x32x16_bf16 v[50:65], v[250:253], v[136:139], v[50:65]

.LBB0_1032:
	v_sub_f32_e32 v49, v100, v0
	v_exp_f32_e32 v49, v49
	v_cmp_lt_f32_e32 vcc, s29, v100
	v_add_u32_e32 v108, s66, v123
	s_nop 0
	v_cndmask_b32_e32 v49, 0, v49, vcc
	v_cmp_lt_f32_e32 vcc, s29, v51
	v_sub_f32_e32 v51, v51, v0
	v_exp_f32_e32 v51, v51
	v_add_f32_e32 v100, 0, v49
	v_cndmask_b32_e32 v51, 0, v51, vcc
	v_cmp_lt_f32_e32 vcc, s29, v52
	v_sub_f32_e32 v52, v52, v0
	v_exp_f32_e32 v52, v52
	v_add_f32_e32 v100, v51, v100
	v_cndmask_b32_e32 v52, 0, v52, vcc
	v_cmp_lt_f32_e32 vcc, s29, v50
	v_sub_f32_e32 v50, v50, v0
	v_exp_f32_e32 v50, v50
	v_add_f32_e32 v100, v52, v100
	v_cndmask_b32_e32 v50, 0, v50, vcc
	v_cmp_lt_f32_e32 vcc, s29, v53
	v_sub_f32_e32 v53, v53, v0
	v_exp_f32_e32 v53, v53
	v_add_f32_e32 v100, v50, v100
	v_cndmask_b32_e32 v53, 0, v53, vcc
	v_cmp_lt_f32_e32 vcc, s29, v54
	v_sub_f32_e32 v54, v54, v0
	v_exp_f32_e32 v54, v54
	v_add_f32_e32 v101, v53, v100
	v_cndmask_b32_e32 v100, 0, v54, vcc
	v_cmp_lt_f32_e32 vcc, s29, v55
	v_sub_f32_e32 v55, v55, v0
	v_exp_f32_e32 v55, v55
	v_add_f32_e32 v54, v100, v101
	v_cndmask_b32_e32 v101, 0, v55, vcc
	v_sub_f32_e32 v55, v56, v0
	v_exp_f32_e32 v55, v55
	v_cmp_lt_f32_e32 vcc, s29, v56
	v_add_f32_e32 v54, v101, v54
	s_nop 0
	v_cndmask_b32_e32 v102, 0, v55, vcc
	v_add_f32_e32 v55, v102, v54
	v_sub_f32_e32 v54, v57, v0
	v_exp_f32_e32 v54, v54
	v_cmp_lt_f32_e32 vcc, s29, v57
	s_nop 1
	v_cndmask_b32_e32 v54, 0, v54, vcc
	v_add_f32_e32 v56, v54, v55
	v_sub_f32_e32 v55, v58, v0
	v_exp_f32_e32 v55, v55
	v_cmp_lt_f32_e32 vcc, s29, v58
	s_nop 1
	v_cndmask_b32_e32 v55, 0, v55, vcc
	v_add_f32_e32 v57, v55, v56
	v_sub_f32_e32 v56, v59, v0
	v_exp_f32_e32 v56, v56
	v_cmp_lt_f32_e32 vcc, s29, v59
	s_nop 1
	v_cndmask_b32_e32 v56, 0, v56, vcc
	v_add_f32_e32 v58, v56, v57
	v_sub_f32_e32 v57, v60, v0
	v_exp_f32_e32 v57, v57
	v_cmp_lt_f32_e32 vcc, s29, v60
	v_sub_f32_e32 v60, v62, v0
	v_exp_f32_e32 v60, v60
	v_cndmask_b32_e32 v57, 0, v57, vcc
	v_add_f32_e32 v59, v57, v58
	v_sub_f32_e32 v58, v61, v0
	v_exp_f32_e32 v58, v58
	v_cmp_lt_f32_e32 vcc, s29, v61
	v_sub_f32_e32 v61, v63, v0
	v_exp_f32_e32 v61, v61
	v_cndmask_b32_e32 v58, 0, v58, vcc
	v_cmp_lt_f32_e32 vcc, s29, v62
	v_sub_f32_e32 v62, v64, v0
	v_exp_f32_e32 v62, v62
	v_cndmask_b32_e32 v60, 0, v60, vcc
	v_cmp_lt_f32_e32 vcc, s29, v63
	v_add_f32_e32 v59, v58, v59
	v_add_f32_e32 v59, v60, v59
	v_cndmask_b32_e32 v61, 0, v61, vcc
	v_cmp_lt_f32_e32 vcc, s29, v64
	v_add_f32_e32 v59, v61, v59
	s_nop 0
	v_cndmask_b32_e32 v62, 0, v62, vcc
	v_cmp_lt_f32_e32 vcc, s29, v34
	v_sub_f32_e32 v34, v34, v0
	v_exp_f32_e32 v34, v34
	v_add_f32_e32 v59, v62, v59
	v_cndmask_b32_e32 v34, 0, v34, vcc
	v_cmp_lt_f32_e32 vcc, s29, v35
	v_sub_f32_e32 v35, v35, v0
	v_exp_f32_e32 v35, v35
	v_add_f32_e32 v59, v34, v59
	v_cndmask_b32_e32 v35, 0, v35, vcc
	v_cmp_lt_f32_e32 vcc, s29, v36
	v_sub_f32_e32 v36, v36, v0
	v_exp_f32_e32 v36, v36
	v_add_f32_e32 v59, v35, v59
	v_cndmask_b32_e32 v36, 0, v36, vcc
	v_cmp_lt_f32_e32 vcc, s29, v37
	v_sub_f32_e32 v37, v37, v0
	v_exp_f32_e32 v37, v37
	v_add_f32_e32 v59, v36, v59
	v_cndmask_b32_e32 v63, 0, v37, vcc
	v_cmp_lt_f32_e32 vcc, s29, v38
	v_sub_f32_e32 v38, v38, v0
	v_exp_f32_e32 v38, v38
	v_add_f32_e32 v37, v63, v59
	v_cndmask_b32_e32 v59, 0, v38, vcc
	v_sub_f32_e32 v38, v39, v0
	v_exp_f32_e32 v38, v38
	v_cmp_lt_f32_e32 vcc, s29, v39
	v_add_f32_e32 v37, v59, v37
	v_sub_f32_e32 v39, v43, v0
	v_cndmask_b32_e32 v64, 0, v38, vcc
	v_sub_f32_e32 v38, v40, v0
	v_exp_f32_e32 v38, v38
	v_cmp_lt_f32_e32 vcc, s29, v40
	v_add_f32_e32 v37, v64, v37
	v_exp_f32_e32 v39, v39
	v_cndmask_b32_e32 v103, 0, v38, vcc
	v_sub_f32_e32 v38, v41, v0
	v_exp_f32_e32 v38, v38
	v_cmp_lt_f32_e32 vcc, s29, v41
	v_add_f32_e32 v37, v103, v37
	v_cvt_pk_bf16_f32 v40, v53, v100
	v_cndmask_b32_e32 v104, 0, v38, vcc
	v_add_f32_e32 v38, v104, v37
	v_sub_f32_e32 v37, v42, v0
	v_exp_f32_e32 v37, v37
	v_cmp_lt_f32_e32 vcc, s29, v42
	v_cvt_pk_bf16_f32 v41, v101, v102
	s_nop 0
	v_cndmask_b32_e32 v37, 0, v37, vcc
	v_cmp_lt_f32_e32 vcc, s29, v43
	v_add_f32_e32 v38, v37, v38
	s_nop 0
	v_cndmask_b32_e32 v105, 0, v39, vcc
	v_sub_f32_e32 v39, v44, v0
	v_exp_f32_e32 v39, v39
	v_cmp_lt_f32_e32 vcc, s29, v44
	v_add_f32_e32 v38, v105, v38
	s_nop 0
	v_cndmask_b32_e32 v106, 0, v39, vcc
	v_sub_f32_e32 v39, v45, v0
	v_exp_f32_e32 v39, v39
	v_cmp_lt_f32_e32 vcc, s29, v45
	v_add_f32_e32 v38, v106, v38
	ds_read_b64_tr_b16 v[238:239], v108 offset:18432
	ds_read_b64_tr_b16 v[240:241], v108 offset:19200
	ds_read_b64_tr_b16 v[242:243], v108 offset:18496
	ds_read_b64_tr_b16 v[244:245], v108 offset:19264
	ds_read_b64_tr_b16 v[246:247], v108 offset:21504
	ds_read_b64_tr_b16 v[248:249], v108 offset:22272
	ds_read_b64_tr_b16 v[250:251], v108 offset:21568
	ds_read_b64_tr_b16 v[252:253], v108 offset:22336
	v_cndmask_b32_e32 v107, 0, v39, vcc
	v_sub_f32_e32 v39, v46, v0
	v_exp_f32_e32 v39, v39
	v_cmp_lt_f32_e32 vcc, s29, v46
	v_add_f32_e32 v38, v107, v38
	s_nop 0
	v_cndmask_b32_e32 v46, 0, v39, vcc
	v_sub_f32_e32 v39, v47, v0
	v_exp_f32_e32 v39, v39
	v_cmp_lt_f32_e32 vcc, s29, v47
	v_add_f32_e32 v38, v46, v38
	s_nop 0
	v_cndmask_b32_e32 v47, 0, v39, vcc
	v_sub_f32_e32 v39, v48, v0
	v_exp_f32_e32 v39, v39
	v_cmp_lt_f32_e32 vcc, s29, v48
	v_add_f32_e32 v38, v47, v38
	s_nop 0
	v_cndmask_b32_e32 v48, 0, v39, vcc
	v_sub_f32_e32 v39, v65, v0
	v_exp_f32_e32 v39, v39
	v_cmp_lt_f32_e32 vcc, s29, v65
	v_add_f32_e32 v38, v48, v38
	s_nop 0
	v_cndmask_b32_e32 v65, 0, v39, vcc
	v_add_f32_e32 v38, v65, v38
	v_add_f32_e32 v134, v38, v132
	v_cvt_pk_bf16_f32 v38, v49, v51
	v_cvt_pk_bf16_f32 v39, v52, v50
	s_nop 0
	s_nop 0
	s_waitcnt lgkmcnt(6)
	v_mfma_f32_32x32x16_bf16 v[2:17], v[238:241], v[38:41], v[2:17]
	ds_read_b64_tr_b16 v[238:239], v108 offset:24576
	ds_read_b64_tr_b16 v[240:241], v108 offset:25344
	s_nop 0
	s_waitcnt lgkmcnt(6)
	v_mfma_f32_32x32x16_bf16 v[18:33], v[242:245], v[38:41], v[18:33]
	ds_read_b64_tr_b16 v[242:243], v108 offset:24640
	ds_read_b64_tr_b16 v[244:245], v108 offset:25408
	v_cvt_pk_bf16_f32 v38, v54, v55
	v_cvt_pk_bf16_f32 v39, v56, v57
	v_cvt_pk_bf16_f32 v40, v58, v60
	v_cvt_pk_bf16_f32 v41, v61, v62
	s_nop 0
	s_nop 0
	s_waitcnt lgkmcnt(6)
	v_mfma_f32_32x32x16_bf16 v[2:17], v[246:249], v[38:41], v[2:17]
	ds_read_b64_tr_b16 v[246:247], v108 offset:27648
	ds_read_b64_tr_b16 v[248:249], v108 offset:28416
	s_nop 0
	s_waitcnt lgkmcnt(6)
	v_mfma_f32_32x32x16_bf16 v[18:33], v[250:253], v[38:41], v[18:33]
	ds_read_b64_tr_b16 v[250:251], v108 offset:27712
	ds_read_b64_tr_b16 v[252:253], v108 offset:28480
	v_cvt_pk_bf16_f32 v38, v34, v35
	v_cvt_pk_bf16_f32 v39, v36, v63
	v_cvt_pk_bf16_f32 v40, v59, v64
	v_cvt_pk_bf16_f32 v41, v103, v104
	v_cvt_pk_bf16_f32 v34, v37, v105
	v_cvt_pk_bf16_f32 v35, v106, v107
	s_nop 0
	s_waitcnt lgkmcnt(6)
	v_mfma_f32_32x32x16_bf16 v[2:17], v[238:241], v[38:41], v[2:17]
	v_cvt_pk_bf16_f32 v36, v46, v47
	v_cvt_pk_bf16_f32 v37, v48, v65
	s_nop 0
	s_waitcnt lgkmcnt(4)
	v_mfma_f32_32x32x16_bf16 v[18:33], v[242:245], v[38:41], v[18:33]
	s_nop 0
	s_waitcnt lgkmcnt(2)
	v_mfma_f32_32x32x16_bf16 v[2:17], v[246:249], v[34:37], v[2:17]
	s_nop 0
	s_waitcnt lgkmcnt(0)
	v_mfma_f32_32x32x16_bf16 v[18:33], v[250:253], v[34:37], v[18:33]
	s_nop 11
	v_mov_b64_e32 v[64:65], v[32:33]
	v_mov_b64_e32 v[62:63], v[30:31]
	v_mov_b64_e32 v[60:61], v[28:29]
	v_mov_b64_e32 v[58:59], v[26:27]
	v_mov_b64_e32 v[56:57], v[24:25]
	v_mov_b64_e32 v[54:55], v[22:23]
	v_mov_b64_e32 v[52:53], v[20:21]
	v_mov_b64_e32 v[50:51], v[18:19]
	v_mov_b64_e32 v[48:49], v[16:17]
	v_mov_b64_e32 v[46:47], v[14:15]
	v_mov_b64_e32 v[44:45], v[12:13]
	v_mov_b64_e32 v[42:43], v[10:11]
	v_mov_b64_e32 v[40:41], v[8:9]
	v_mov_b64_e32 v[38:39], v[6:7]
	v_mov_b64_e32 v[36:37], v[4:5]
	v_mov_b64_e32 v[34:35], v[2:3]

.LBB0_1063:
	v_mul_f32_e64 v208, -v118, v208
	v_sub_f32_e32 v208, v0, v208
	v_cndmask_b32_e64 v208, v146, v208, s[12:13]
	v_sub_f32_e32 v207, v207, v208
	v_exp_f32_e32 v207, v207
	v_sub_f32_e32 v206, v206, v208
	v_exp_f32_e32 v206, v206
	v_sub_f32_e32 v205, v205, v208
	v_exp_f32_e32 v205, v205
	v_sub_f32_e32 v204, v204, v208
	v_exp_f32_e32 v204, v204
	v_sub_f32_e32 v203, v203, v208
	v_add_f32_e32 v209, 0, v207
	v_exp_f32_e32 v203, v203
	v_sub_f32_e32 v202, v202, v208
	v_add_f32_e32 v209, v206, v209
	v_exp_f32_e32 v202, v202
	v_sub_f32_e32 v201, v201, v208
	v_add_f32_e32 v209, v205, v209
	v_exp_f32_e32 v201, v201
	v_sub_f32_e32 v200, v200, v208
	v_add_f32_e32 v209, v204, v209
	v_exp_f32_e32 v200, v200
	v_sub_f32_e32 v199, v199, v208
	v_add_f32_e32 v209, v203, v209
	v_exp_f32_e32 v199, v199
	v_sub_f32_e32 v198, v198, v208
	v_add_f32_e32 v209, v202, v209
	v_exp_f32_e32 v198, v198
	v_sub_f32_e32 v197, v197, v208
	v_add_f32_e32 v209, v201, v209
	v_exp_f32_e32 v197, v197
	v_sub_f32_e32 v196, v196, v208
	v_add_f32_e32 v209, v200, v209
	v_exp_f32_e32 v196, v196
	v_sub_f32_e32 v195, v195, v208
	v_add_f32_e32 v209, v199, v209
	v_exp_f32_e32 v195, v195
	v_sub_f32_e32 v194, v194, v208
	v_add_f32_e32 v209, v198, v209
	v_exp_f32_e32 v194, v194
	v_sub_f32_e32 v193, v193, v208
	v_add_f32_e32 v209, v197, v209
	v_exp_f32_e32 v193, v193
	v_sub_f32_e32 v192, v192, v208
	v_add_f32_e32 v209, v196, v209
	v_exp_f32_e32 v192, v192
	v_sub_f32_e32 v191, v191, v208
	v_add_f32_e32 v209, v195, v209
	v_exp_f32_e32 v191, v191
	v_sub_f32_e32 v190, v190, v208
	v_add_f32_e32 v209, v194, v209
	v_exp_f32_e32 v190, v190
	v_sub_f32_e32 v189, v189, v208
	v_add_f32_e32 v209, v193, v209
	v_exp_f32_e32 v189, v189
	v_sub_f32_e32 v188, v188, v208
	v_add_f32_e32 v209, v192, v209
	v_exp_f32_e32 v188, v188
	v_sub_f32_e32 v187, v187, v208
	v_add_f32_e32 v209, v191, v209
	v_exp_f32_e32 v187, v187
	v_sub_f32_e32 v186, v186, v208
	v_add_f32_e32 v209, v190, v209
	v_exp_f32_e32 v186, v186
	v_sub_f32_e32 v184, v184, v208
	v_add_f32_e32 v209, v189, v209
	v_exp_f32_e32 v210, v184
	v_add_f32_e32 v209, v188, v209
	v_add_f32_e32 v209, v187, v209
	v_add_f32_e32 v209, v186, v209
	v_sub_f32_e32 v183, v183, v208
	v_add_f32_e32 v184, v210, v209
	v_exp_f32_e32 v209, v183
	v_sub_f32_e32 v182, v182, v208
	v_exp_f32_e32 v211, v182
	v_sub_f32_e32 v181, v181, v208
	v_exp_f32_e32 v181, v181
	v_sub_f32_e32 v139, v139, v208
	v_exp_f32_e32 v212, v139
	v_sub_f32_e32 v138, v138, v208
	v_add_f32_e32 v183, v209, v184
	v_exp_f32_e32 v213, v138
	v_sub_f32_e32 v137, v137, v208
	v_add_f32_e32 v182, v211, v183
	v_exp_f32_e32 v214, v137
	v_sub_f32_e32 v136, v136, v208
	v_add_f32_e32 v182, v181, v182
	v_exp_f32_e32 v215, v136
	v_sub_f32_e32 v135, v135, v208
	v_add_f32_e32 v139, v212, v182
	v_exp_f32_e32 v135, v135
	v_sub_f32_e32 v133, v133, v208
	v_add_f32_e32 v138, v213, v139
	v_exp_f32_e32 v208, v133
	v_add_f32_e32 v137, v214, v138
	v_add_f32_e32 v136, v215, v137
	v_add_f32_e32 v136, v135, v136
	v_add_f32_e32 v133, v208, v136
	v_add_u32_e32 v216, s2, v123
	v_add_f32_e32 v133, v133, v185
	ds_read_b64_tr_b16 v[238:239], v216 offset:18432
	ds_read_b64_tr_b16 v[240:241], v216 offset:19200
	ds_read_b64_tr_b16 v[242:243], v216 offset:18496
	ds_read_b64_tr_b16 v[244:245], v216 offset:19264
	ds_read_b64_tr_b16 v[246:247], v216 offset:21504
	ds_read_b64_tr_b16 v[248:249], v216 offset:22272
	ds_read_b64_tr_b16 v[250:251], v216 offset:21568
	ds_read_b64_tr_b16 v[252:253], v216 offset:22336
	v_cvt_pk_bf16_f32 v136, v207, v206
	v_cvt_pk_bf16_f32 v137, v205, v204
	v_cvt_pk_bf16_f32 v138, v203, v202
	v_cvt_pk_bf16_f32 v139, v201, v200
	s_mov_b64 s[12:13], 0
	s_nop 0
	s_waitcnt lgkmcnt(6)
	v_mfma_f32_32x32x16_bf16 v[36:51], v[238:241], v[136:139], v[36:51]
	ds_read_b64_tr_b16 v[238:239], v216 offset:24576
	ds_read_b64_tr_b16 v[240:241], v216 offset:25344
	s_nop 0
	s_waitcnt lgkmcnt(6)
	v_mfma_f32_32x32x16_bf16 v[52:67], v[242:245], v[136:139], v[52:67]
	ds_read_b64_tr_b16 v[242:243], v216 offset:24640
	ds_read_b64_tr_b16 v[244:245], v216 offset:25408
	v_cvt_pk_bf16_f32 v136, v199, v198
	v_cvt_pk_bf16_f32 v137, v197, v196
	v_cvt_pk_bf16_f32 v138, v195, v194
	v_cvt_pk_bf16_f32 v139, v193, v192
	s_nop 0
	s_nop 0
	s_waitcnt lgkmcnt(6)
	v_mfma_f32_32x32x16_bf16 v[36:51], v[246:249], v[136:139], v[36:51]
	ds_read_b64_tr_b16 v[246:247], v216 offset:27648
	ds_read_b64_tr_b16 v[248:249], v216 offset:28416
	s_nop 0
	s_waitcnt lgkmcnt(6)
	v_mfma_f32_32x32x16_bf16 v[52:67], v[250:253], v[136:139], v[52:67]
	ds_read_b64_tr_b16 v[250:251], v216 offset:27712
	ds_read_b64_tr_b16 v[252:253], v216 offset:28480
	v_cvt_pk_bf16_f32 v136, v191, v190
	v_cvt_pk_bf16_f32 v137, v189, v188
	v_cvt_pk_bf16_f32 v138, v187, v186
	v_cvt_pk_bf16_f32 v139, v210, v209
	s_nop 0
	s_nop 0
	s_waitcnt lgkmcnt(6)
	v_mfma_f32_32x32x16_bf16 v[36:51], v[238:241], v[136:139], v[36:51]
	s_nop 0
	s_waitcnt lgkmcnt(4)
	v_mfma_f32_32x32x16_bf16 v[52:67], v[242:245], v[136:139], v[52:67]
	v_cvt_pk_bf16_f32 v136, v211, v181
	v_cvt_pk_bf16_f32 v137, v212, v213
	v_cvt_pk_bf16_f32 v138, v214, v215
	v_cvt_pk_bf16_f32 v139, v135, v208
	s_nop 0
	s_nop 0
	s_waitcnt lgkmcnt(2)
	v_mfma_f32_32x32x16_bf16 v[36:51], v[246:249], v[136:139], v[36:51]
	s_nop 0
	s_waitcnt lgkmcnt(0)
	v_mfma_f32_32x32x16_bf16 v[52:67], v[250:253], v[136:139], v[52:67]

.LBB0_1067:
	v_sub_f32_e32 v50, v100, v0
	v_exp_f32_e32 v50, v50
	v_cmp_lt_f32_e32 vcc, s29, v100
	v_sub_f32_e32 v51, v53, v0
	v_exp_f32_e32 v51, v51
	v_cndmask_b32_e32 v50, 0, v50, vcc
	v_cmp_lt_f32_e32 vcc, s29, v53
	v_sub_f32_e32 v53, v54, v0
	v_exp_f32_e32 v53, v53
	v_cndmask_b32_e32 v51, 0, v51, vcc
	v_cmp_lt_f32_e32 vcc, s29, v54
	v_add_f32_e32 v100, 0, v50
	v_add_f32_e32 v100, v51, v100
	v_cndmask_b32_e32 v53, 0, v53, vcc
	v_cmp_lt_f32_e32 vcc, s29, v52
	v_sub_f32_e32 v52, v52, v0
	v_exp_f32_e32 v52, v52
	v_add_f32_e32 v54, v53, v100
	v_cndmask_b32_e32 v52, 0, v52, vcc
	v_add_f32_e32 v100, v52, v54
	v_sub_f32_e32 v54, v55, v0
	v_exp_f32_e32 v54, v54
	v_cmp_lt_f32_e32 vcc, s29, v55
	s_nop 1
	v_cndmask_b32_e32 v54, 0, v54, vcc
	v_cmp_lt_f32_e32 vcc, s29, v56
	v_sub_f32_e32 v56, v56, v0
	v_exp_f32_e32 v56, v56
	v_add_f32_e32 v55, v54, v100
	v_cndmask_b32_e32 v56, 0, v56, vcc
	v_cmp_lt_f32_e32 vcc, s29, v57
	v_sub_f32_e32 v57, v57, v0
	v_exp_f32_e32 v57, v57
	v_add_f32_e32 v55, v56, v55
	v_cndmask_b32_e32 v100, 0, v57, vcc
	v_sub_f32_e32 v57, v58, v0
	v_exp_f32_e32 v57, v57
	v_cmp_lt_f32_e32 vcc, s29, v58
	v_add_f32_e32 v55, v100, v55
	s_nop 0
	v_cndmask_b32_e32 v102, 0, v57, vcc
	v_add_f32_e32 v57, v102, v55
	v_sub_f32_e32 v55, v59, v0
	v_exp_f32_e32 v55, v55
	v_cmp_lt_f32_e32 vcc, s29, v59
	s_nop 1
	v_cndmask_b32_e32 v55, 0, v55, vcc
	v_add_f32_e32 v58, v55, v57
	v_sub_f32_e32 v57, v60, v0
	v_exp_f32_e32 v57, v57
	v_cmp_lt_f32_e32 vcc, s29, v60
	s_nop 1
	v_cndmask_b32_e32 v57, 0, v57, vcc
	v_add_f32_e32 v59, v57, v58
	v_sub_f32_e32 v58, v61, v0
	v_exp_f32_e32 v58, v58
	v_cmp_lt_f32_e32 vcc, s29, v61
	s_nop 1
	v_cndmask_b32_e32 v58, 0, v58, vcc
	v_add_f32_e32 v60, v58, v59
	v_sub_f32_e32 v59, v62, v0
	v_exp_f32_e32 v59, v59
	v_cmp_lt_f32_e32 vcc, s29, v62
	v_sub_f32_e32 v62, v64, v0
	v_exp_f32_e32 v62, v62
	v_cndmask_b32_e32 v59, 0, v59, vcc
	v_add_f32_e32 v61, v59, v60
	v_sub_f32_e32 v60, v63, v0
	v_exp_f32_e32 v60, v60
	v_cmp_lt_f32_e32 vcc, s29, v63
	v_sub_f32_e32 v63, v65, v0
	v_exp_f32_e32 v63, v63
	v_cndmask_b32_e32 v60, 0, v60, vcc
	v_cmp_lt_f32_e32 vcc, s29, v64
	v_sub_f32_e32 v64, v66, v0
	v_exp_f32_e32 v64, v64
	v_cndmask_b32_e32 v62, 0, v62, vcc
	v_cmp_lt_f32_e32 vcc, s29, v65
	v_add_f32_e32 v61, v60, v61
	v_add_f32_e32 v61, v62, v61
	v_cndmask_b32_e32 v63, 0, v63, vcc
	v_cmp_lt_f32_e32 vcc, s29, v66
	v_add_f32_e32 v61, v63, v61
	s_nop 0
	v_cndmask_b32_e32 v64, 0, v64, vcc
	v_cmp_lt_f32_e32 vcc, s29, v36
	v_sub_f32_e32 v36, v36, v0
	v_exp_f32_e32 v36, v36
	v_add_f32_e32 v61, v64, v61
	v_cndmask_b32_e32 v36, 0, v36, vcc
	v_cmp_lt_f32_e32 vcc, s29, v37
	v_sub_f32_e32 v37, v37, v0
	v_exp_f32_e32 v37, v37
	v_add_f32_e32 v61, v36, v61
	v_cndmask_b32_e32 v37, 0, v37, vcc
	v_cmp_lt_f32_e32 vcc, s29, v38
	v_sub_f32_e32 v38, v38, v0
	v_exp_f32_e32 v38, v38
	v_add_f32_e32 v61, v37, v61
	v_cndmask_b32_e32 v38, 0, v38, vcc
	v_cmp_lt_f32_e32 vcc, s29, v39
	v_sub_f32_e32 v39, v39, v0
	v_exp_f32_e32 v39, v39
	v_add_f32_e32 v61, v38, v61
	v_cndmask_b32_e32 v65, 0, v39, vcc
	v_cmp_lt_f32_e32 vcc, s29, v40
	v_sub_f32_e32 v40, v40, v0
	v_exp_f32_e32 v40, v40
	v_add_f32_e32 v39, v65, v61
	v_cndmask_b32_e32 v61, 0, v40, vcc
	v_sub_f32_e32 v40, v41, v0
	v_exp_f32_e32 v40, v40
	v_cmp_lt_f32_e32 vcc, s29, v41
	v_add_f32_e32 v39, v61, v39
	v_sub_f32_e32 v41, v45, v0
	v_cndmask_b32_e32 v66, 0, v40, vcc
	v_sub_f32_e32 v40, v42, v0
	v_exp_f32_e32 v40, v40
	v_cmp_lt_f32_e32 vcc, s29, v42
	v_add_f32_e32 v39, v66, v39
	v_exp_f32_e32 v41, v41
	v_cndmask_b32_e32 v103, 0, v40, vcc
	v_sub_f32_e32 v40, v43, v0
	v_exp_f32_e32 v40, v40
	v_cmp_lt_f32_e32 vcc, s29, v43
	v_add_f32_e32 v39, v103, v39
	v_cvt_pk_bf16_f32 v42, v54, v56
	v_cndmask_b32_e32 v104, 0, v40, vcc
	v_add_f32_e32 v40, v104, v39
	v_sub_f32_e32 v39, v44, v0
	v_exp_f32_e32 v39, v39
	v_cmp_lt_f32_e32 vcc, s29, v44
	v_cvt_pk_bf16_f32 v43, v100, v102
	s_nop 0
	v_cndmask_b32_e32 v39, 0, v39, vcc
	v_cmp_lt_f32_e32 vcc, s29, v45
	v_add_f32_e32 v40, v39, v40
	s_nop 0
	v_cndmask_b32_e32 v105, 0, v41, vcc
	v_sub_f32_e32 v41, v46, v0
	v_exp_f32_e32 v41, v41
	v_cmp_lt_f32_e32 vcc, s29, v46
	v_add_f32_e32 v40, v105, v40
	s_nop 0
	v_cndmask_b32_e32 v106, 0, v41, vcc
	v_sub_f32_e32 v41, v47, v0
	v_exp_f32_e32 v41, v41
	v_cmp_lt_f32_e32 vcc, s29, v47
	v_add_f32_e32 v40, v106, v40
	s_nop 0
	v_cndmask_b32_e32 v107, 0, v41, vcc
	v_sub_f32_e32 v41, v48, v0
	v_exp_f32_e32 v41, v41
	v_cmp_lt_f32_e32 vcc, s29, v48
	v_add_f32_e32 v40, v107, v40
	s_nop 0
	v_cndmask_b32_e32 v48, 0, v41, vcc
	v_sub_f32_e32 v41, v49, v0
	v_exp_f32_e32 v41, v41
	v_cmp_lt_f32_e32 vcc, s29, v49
	v_add_f32_e32 v40, v48, v40
	s_nop 0
	v_cndmask_b32_e32 v49, 0, v41, vcc
	v_sub_f32_e32 v41, v67, v0
	v_exp_f32_e32 v41, v41
	v_cmp_lt_f32_e32 vcc, s29, v67
	v_add_f32_e32 v40, v49, v40
	s_nop 0
	v_cndmask_b32_e32 v67, 0, v41, vcc
	v_sub_f32_e32 v41, v101, v0
	v_exp_f32_e32 v41, v41
	v_cmp_lt_f32_e32 vcc, s29, v101
	v_add_f32_e32 v40, v67, v40
	s_nop 0
	v_cndmask_b32_e32 v101, 0, v41, vcc
	v_add_f32_e32 v40, v101, v40
	v_add_f32_e32 v133, v40, v34
	v_add_u32_e32 v34, s2, v123
	ds_read_b64_tr_b16 v[238:239], v34 offset:18432
	ds_read_b64_tr_b16 v[240:241], v34 offset:19200
	ds_read_b64_tr_b16 v[242:243], v34 offset:18496
	ds_read_b64_tr_b16 v[244:245], v34 offset:19264
	ds_read_b64_tr_b16 v[246:247], v34 offset:21504
	ds_read_b64_tr_b16 v[248:249], v34 offset:22272
	ds_read_b64_tr_b16 v[250:251], v34 offset:21568
	ds_read_b64_tr_b16 v[252:253], v34 offset:22336
	v_cvt_pk_bf16_f32 v40, v50, v51
	v_cvt_pk_bf16_f32 v41, v53, v52
	s_nop 0
	s_nop 0
	s_waitcnt lgkmcnt(6)
	v_mfma_f32_32x32x16_bf16 v[2:17], v[238:241], v[40:43], v[2:17]
	ds_read_b64_tr_b16 v[238:239], v34 offset:24576
	ds_read_b64_tr_b16 v[240:241], v34 offset:25344
	s_nop 0
	s_waitcnt lgkmcnt(6)
	v_mfma_f32_32x32x16_bf16 v[18:33], v[242:245], v[40:43], v[18:33]
	ds_read_b64_tr_b16 v[242:243], v34 offset:24640
	ds_read_b64_tr_b16 v[244:245], v34 offset:25408
	v_cvt_pk_bf16_f32 v40, v55, v57
	v_cvt_pk_bf16_f32 v41, v58, v59
	v_cvt_pk_bf16_f32 v42, v60, v62
	v_cvt_pk_bf16_f32 v43, v63, v64
	s_nop 0
	s_nop 0
	s_waitcnt lgkmcnt(6)
	v_mfma_f32_32x32x16_bf16 v[2:17], v[246:249], v[40:43], v[2:17]
	ds_read_b64_tr_b16 v[246:247], v34 offset:27648
	ds_read_b64_tr_b16 v[248:249], v34 offset:28416
	s_nop 0
	s_waitcnt lgkmcnt(6)
	v_mfma_f32_32x32x16_bf16 v[18:33], v[250:253], v[40:43], v[18:33]
	ds_read_b64_tr_b16 v[250:251], v34 offset:27712
	ds_read_b64_tr_b16 v[252:253], v34 offset:28480
	v_cvt_pk_bf16_f32 v40, v36, v37
	v_cvt_pk_bf16_f32 v41, v38, v65
	v_cvt_pk_bf16_f32 v42, v61, v66
	v_cvt_pk_bf16_f32 v43, v103, v104
	v_cvt_pk_bf16_f32 v36, v39, v105
	v_cvt_pk_bf16_f32 v37, v106, v107
	s_nop 0
	s_waitcnt lgkmcnt(6)
	v_mfma_f32_32x32x16_bf16 v[2:17], v[238:241], v[40:43], v[2:17]
	v_cvt_pk_bf16_f32 v38, v48, v49
	v_cvt_pk_bf16_f32 v39, v67, v101
	s_nop 0
	s_waitcnt lgkmcnt(4)
	v_mfma_f32_32x32x16_bf16 v[18:33], v[242:245], v[40:43], v[18:33]
	s_nop 0
	s_waitcnt lgkmcnt(2)
	v_mfma_f32_32x32x16_bf16 v[2:17], v[246:249], v[36:39], v[2:17]
	s_nop 0
	s_waitcnt lgkmcnt(0)
	v_mfma_f32_32x32x16_bf16 v[18:33], v[250:253], v[36:39], v[18:33]
	s_nop 11
	v_mov_b64_e32 v[66:67], v[32:33]
	v_mov_b64_e32 v[64:65], v[30:31]
	v_mov_b64_e32 v[62:63], v[28:29]
	v_mov_b64_e32 v[60:61], v[26:27]
	v_mov_b64_e32 v[58:59], v[24:25]
	v_mov_b64_e32 v[56:57], v[22:23]
	v_mov_b64_e32 v[54:55], v[20:21]
	v_mov_b64_e32 v[52:53], v[18:19]
	v_mov_b64_e32 v[50:51], v[16:17]
	v_mov_b64_e32 v[48:49], v[14:15]
	v_mov_b64_e32 v[46:47], v[12:13]
	v_mov_b64_e32 v[44:45], v[10:11]
	v_mov_b64_e32 v[42:43], v[8:9]
	v_mov_b64_e32 v[40:41], v[6:7]
	v_mov_b64_e32 v[38:39], v[4:5]
	v_mov_b64_e32 v[36:37], v[2:3]
